# strategy 'back-edge rotation' (7.11) on the four GEMM K loops: trip counter, pointer bumps, next-trip scalar selects and exit test moved ahead of the loop-back barrier
# baseline (speedup 1.0000x reference)
; #define PG8_STAGE(bufoff, gbase, voff) do { _Pragma("unroll") for (int _i = 0; _i < 2; ++_i) \
;         __builtin_amdgcn_global_load_lds((const unsigned*)((const char*)(gbase) + (voff)[_i]), (LAS unsigned*)(lds + (bufoff) + ldsw + _i * 8192), 16, 0, 0); } while (0)
; #define PG8_LDA(dst, b, h) do { _Pragma("unroll") for (int m = 0; m < 4; ++m) _Pragma("unroll") for (int k = 0; k < 2; ++k) dst[m][k] = *(const LAS bf16x8*)(lds + PG8_SA(b, h) + aoff + m * 2048 + k * 1024); } while (0)
; #define PG8_LDB(dst, b, h) do { _Pragma("unroll") for (int n = 0; n < 2; ++n) _Pragma("unroll") for (int k = 0; k < 2; ++k) dst[n][k] = *(const LAS bf16x8*)(lds + PG8_SB(b, h) + boff + n * 2048 + k * 1024); } while (0)
; #define PG8_MMA(ai, bj, At, Bt) do { __builtin_amdgcn_s_setprio(1); _Pragma("unroll") for (int m = 0; m < 4; ++m) _Pragma("unroll") for (int n = 0; n < 2; ++n) _Pragma("unroll") for (int k = 0; k < 2; ++k) \
;         acc[ai][bj][m][n] = __builtin_amdgcn_mfma_f32_16x16x32_bf16(Bt[n][k], At[m][k], acc[ai][bj][m][n], 0, 0, 0); __builtin_amdgcn_s_setprio(0); } while (0)
; #define PG8_WAIT_V(n) asm volatile("s_waitcnt vmcnt(" #n ")" ::: "memory")
; #define PG8_WAIT_L(n) asm volatile("s_waitcnt lgkmcnt(" #n ")" ::: "memory")
; #define PG8_BAR __builtin_amdgcn_s_barrier()
; #define PG8_SCHED __builtin_amdgcn_sched_barrier(0)
;     ...
;         for (int t = 0; t < nt; t += 2) {
;             const bool last = (t == nt - 2);
;             const char* a1 = cA + (size_t)(t + 1) * kstep;
;             const char* a2 = last ? nA : cA + (size_t)(t + 2) * kstep; const char* b2 = last ? nB : cB + (size_t)(t + 2) * kstep;
;             const char* a3 = a2 + kstep; const char* b3 = b2 + kstep;
;             if constexpr (NB == 2) {
;             PG8_LDB(B0, 0, 0); PG8_LDB(B1, 0, 1); PG8_SCHED; PG8_LDA(At, 0, 0); PG8_STAGE(PG8_SA(1, 1), a1 + hstep, voffA);
;             PG8_WAIT_V(8); PG8_WAIT_L(0); PG8_BAR; PG8_MMA(0, 0, At, B0); PG8_MMA(0, 1, At, B1); PG8_BAR; PG8_SCHED;
;             PG8_LDA(At, 0, 1); PG8_STAGE(PG8_SB(0, 0), b2, voffB); PG8_STAGE(PG8_SB(0, 1), b2 + hstep, voffB); PG8_STAGE(PG8_SA(0, 0), a2, voffA);
;             PG8_WAIT_V(8); PG8_WAIT_L(0); PG8_BAR; PG8_MMA(1, 0, At, B0); PG8_MMA(1, 1, At, B1); PG8_BAR; PG8_SCHED;
.LBB0_129:
	s_add_u32 s34, s26, 0xfff80080
	s_addc_u32 s35, s27, -1
	s_add_i32 s39, 0, 0x10000
	s_cmp_eq_u32 s38, 28
	s_cselect_b32 s37, s3, s35
	s_cselect_b32 s36, s5, s34
	s_cselect_b32 s35, s28, s33
	s_cselect_b32 s34, s30, s31
	s_add_i32 s43, 0, 0x14000
.Lkrot_0:
	v_add_u32_e32 v34, s39, v151
	ds_read_b128 v[144:147], v34
	ds_read_b128 v[158:161], v34 offset:1024
	ds_read_b128 v[180:183], v34 offset:2048
	ds_read_b128 v[184:187], v34 offset:3072
	v_add_u32_e32 v34, s43, v151
	ds_read_b128 v[188:191], v34
	ds_read_b128 v[192:195], v34 offset:1024
	ds_read_b128 v[196:199], v34 offset:2048
	ds_read_b128 v[200:203], v34 offset:3072
	v_lshl_add_u64 v[148:149], s[26:27], 0, v[140:141]
	s_add_i32 m0, s52, 0xc000
	ds_read_b128 v[204:207], v157
	ds_read_b128 v[224:227], v157 offset:1024
	ds_read_b128 v[228:231], v157 offset:2048
	ds_read_b128 v[232:235], v157 offset:3072
	ds_read_b128 v[236:239], v157 offset:4096
	ds_read_b128 v[240:243], v157 offset:5120
	ds_read_b128 v[244:247], v157 offset:6144
	ds_read_b128 v[162:165], v157 offset:7168
	global_load_lds_dwordx4 v[148:149], off
	v_lshl_add_u64 v[148:149], s[26:27], 0, v[142:143]
	s_add_i32 m0, s52, 0xe000
	s_nop 0
	global_load_lds_dwordx4 v[148:149], off
	s_waitcnt vmcnt(8)
	s_waitcnt lgkmcnt(0)
	s_barrier
	s_setprio 1
	s_waitcnt lgkmcnt(0)
	v_mfma_f32_16x16x32_bf16 v[128:131], v[144:147], v[204:207], v[128:131]
	v_mfma_f32_16x16x32_bf16 v[124:127], v[180:183], v[204:207], v[124:127]
	v_mfma_f32_16x16x32_bf16 v[120:123], v[144:147], v[228:231], v[120:123]
	v_mfma_f32_16x16x32_bf16 v[112:115], v[180:183], v[228:231], v[112:115]
	v_mfma_f32_16x16x32_bf16 v[104:107], v[144:147], v[236:239], v[104:107]
	v_mfma_f32_16x16x32_bf16 v[96:99], v[180:183], v[236:239], v[96:99]
	v_mfma_f32_16x16x32_bf16 v[88:91], v[144:147], v[244:247], v[88:91]
	v_mfma_f32_16x16x32_bf16 v[80:83], v[180:183], v[244:247], v[80:83]
	v_mfma_f32_16x16x32_bf16 v[128:131], v[158:161], v[224:227], v[128:131]
	v_mfma_f32_16x16x32_bf16 v[124:127], v[184:187], v[224:227], v[124:127]
	v_mfma_f32_16x16x32_bf16 v[120:123], v[158:161], v[232:235], v[120:123]
	v_mfma_f32_16x16x32_bf16 v[112:115], v[184:187], v[232:235], v[112:115]
	v_mfma_f32_16x16x32_bf16 v[104:107], v[158:161], v[240:243], v[104:107]
	v_mfma_f32_16x16x32_bf16 v[96:99], v[184:187], v[240:243], v[96:99]
	v_mfma_f32_16x16x32_bf16 v[88:91], v[158:161], v[162:165], v[88:91]
	v_mfma_f32_16x16x32_bf16 v[80:83], v[184:187], v[162:165], v[80:83]
	s_setprio 0
	s_setprio 1
	v_mfma_f32_16x16x32_bf16 v[116:119], v[188:191], v[204:207], v[116:119]
	v_mfma_f32_16x16x32_bf16 v[108:111], v[196:199], v[204:207], v[108:111]
	v_mfma_f32_16x16x32_bf16 v[100:103], v[188:191], v[228:231], v[100:103]
	v_mfma_f32_16x16x32_bf16 v[92:95], v[196:199], v[228:231], v[92:95]
	v_mfma_f32_16x16x32_bf16 v[84:87], v[188:191], v[236:239], v[84:87]
	v_mfma_f32_16x16x32_bf16 v[76:79], v[196:199], v[236:239], v[76:79]
	v_mfma_f32_16x16x32_bf16 v[72:75], v[188:191], v[244:247], v[72:75]
	v_mfma_f32_16x16x32_bf16 v[68:71], v[196:199], v[244:247], v[68:71]
	v_mfma_f32_16x16x32_bf16 v[116:119], v[192:195], v[224:227], v[116:119]
	v_mfma_f32_16x16x32_bf16 v[108:111], v[200:203], v[224:227], v[108:111]
	v_mfma_f32_16x16x32_bf16 v[100:103], v[192:195], v[232:235], v[100:103]
	v_mfma_f32_16x16x32_bf16 v[92:95], v[200:203], v[232:235], v[92:95]
	v_mfma_f32_16x16x32_bf16 v[84:87], v[192:195], v[240:243], v[84:87]
	v_mfma_f32_16x16x32_bf16 v[76:79], v[200:203], v[240:243], v[76:79]
	v_mfma_f32_16x16x32_bf16 v[72:75], v[192:195], v[162:165], v[72:75]
	v_mfma_f32_16x16x32_bf16 v[68:71], v[200:203], v[162:165], v[68:71]
	s_setprio 0
	s_barrier
	s_add_i32 s39, s39, s51
	v_lshl_add_u64 v[148:149], s[34:35], 0, v[134:135]
	s_mov_b32 m0, s39
	ds_read_b128 v[162:165], v157 offset:16384
	ds_read_b128 v[204:207], v157 offset:17408
	ds_read_b128 v[224:227], v157 offset:18432
	ds_read_b128 v[228:231], v157 offset:19456
	ds_read_b128 v[232:235], v157 offset:20480
	ds_read_b128 v[236:239], v157 offset:21504
	ds_read_b128 v[240:243], v157 offset:22528
	ds_read_b128 v[244:247], v157 offset:23552
	global_load_lds_dwordx4 v[148:149], off
	s_add_i32 m0, s39, 0x2000
	s_add_u32 s58, s34, 0x80000
	v_lshl_add_u64 v[248:249], s[34:35], 0, v[138:139]
	s_addc_u32 s59, s35, 0
	s_add_i32 s39, s43, s51
	global_load_lds_dwordx4 v[248:249], off
	v_lshl_add_u64 v[222:223], s[58:59], 0, v[134:135]
	s_mov_b32 m0, s39
	v_lshl_add_u64 v[166:167], s[36:37], 0, v[136:137]
	global_load_lds_dwordx4 v[222:223], off
	v_lshl_add_u64 v[222:223], s[58:59], 0, v[138:139]
	s_add_i32 m0, s39, 0x2000
	s_nop 0
	global_load_lds_dwordx4 v[222:223], off
	v_lshl_add_u64 v[222:223], s[36:37], 0, v[132:133]
	s_mov_b32 m0, s52
	s_nop 0
	global_load_lds_dwordx4 v[222:223], off
	s_mov_b32 m0, s53
	s_nop 0
	global_load_lds_dwordx4 v[166:167], off
	s_waitcnt vmcnt(8)
	s_waitcnt lgkmcnt(0)
	s_barrier
; #define PG8_STAGE(bufoff, gbase, voff) do { _Pragma("unroll") for (int _i = 0; _i < 2; ++_i) \
;         __builtin_amdgcn_global_load_lds((const unsigned*)((const char*)(gbase) + (voff)[_i]), (LAS unsigned*)(lds + (bufoff) + ldsw + _i * 8192), 16, 0, 0); } while (0)
; #define PG8_LDA(dst, b, h) do { _Pragma("unroll") for (int m = 0; m < 4; ++m) _Pragma("unroll") for (int k = 0; k < 2; ++k) dst[m][k] = *(const LAS bf16x8*)(lds + PG8_SA(b, h) + aoff + m * 2048 + k * 1024); } while (0)
; #define PG8_LDB(dst, b, h) do { _Pragma("unroll") for (int n = 0; n < 2; ++n) _Pragma("unroll") for (int k = 0; k < 2; ++k) dst[n][k] = *(const LAS bf16x8*)(lds + PG8_SB(b, h) + boff + n * 2048 + k * 1024); } while (0)
; #define PG8_MMA(ai, bj, At, Bt) do { __builtin_amdgcn_s_setprio(1); _Pragma("unroll") for (int m = 0; m < 4; ++m) _Pragma("unroll") for (int n = 0; n < 2; ++n) _Pragma("unroll") for (int k = 0; k < 2; ++k) \
;         acc[ai][bj][m][n] = __builtin_amdgcn_mfma_f32_16x16x32_bf16(Bt[n][k], At[m][k], acc[ai][bj][m][n], 0, 0, 0); __builtin_amdgcn_s_setprio(0); } while (0)
; #define PG8_WAIT_V(n) asm volatile("s_waitcnt vmcnt(" #n ")" ::: "memory")
; #define PG8_WAIT_L(n) asm volatile("s_waitcnt lgkmcnt(" #n ")" ::: "memory")
; #define PG8_BAR __builtin_amdgcn_s_barrier()
; #define PG8_SCHED __builtin_amdgcn_sched_barrier(0)
;     ...
;             PG8_WAIT_V(8); PG8_WAIT_L(0); PG8_BAR; PG8_MMA(1, 0, At, B0); PG8_MMA(1, 1, At, B1); PG8_BAR; PG8_SCHED;
;             PG8_LDB(B0, 1, 0); PG8_LDB(B1, 1, 1); PG8_SCHED; PG8_LDA(At, 1, 0); PG8_STAGE(PG8_SA(0, 1), a2 + hstep, voffA);
;             PG8_WAIT_V(8); PG8_WAIT_L(0); PG8_BAR; PG8_MMA(0, 0, At, B0); PG8_MMA(0, 1, At, B1); PG8_BAR; PG8_SCHED;
	s_setprio 1
	s_waitcnt lgkmcnt(0)
	v_mfma_f32_16x16x32_bf16 v[64:67], v[144:147], v[162:165], v[64:67]
	v_mfma_f32_16x16x32_bf16 v[60:63], v[180:183], v[162:165], v[60:63]
	v_mfma_f32_16x16x32_bf16 v[56:59], v[144:147], v[224:227], v[56:59]
	v_mfma_f32_16x16x32_bf16 v[48:51], v[180:183], v[224:227], v[48:51]
	v_mfma_f32_16x16x32_bf16 v[40:43], v[144:147], v[232:235], v[40:43]
	v_mfma_f32_16x16x32_bf16 v[30:33], v[180:183], v[232:235], v[30:33]
	v_mfma_f32_16x16x32_bf16 v[22:25], v[144:147], v[240:243], v[22:25]
	v_mfma_f32_16x16x32_bf16 v[14:17], v[180:183], v[240:243], v[14:17]
	v_mfma_f32_16x16x32_bf16 v[64:67], v[158:161], v[204:207], v[64:67]
	v_mfma_f32_16x16x32_bf16 v[60:63], v[184:187], v[204:207], v[60:63]
	v_mfma_f32_16x16x32_bf16 v[56:59], v[158:161], v[228:231], v[56:59]
	v_mfma_f32_16x16x32_bf16 v[48:51], v[184:187], v[228:231], v[48:51]
	v_mfma_f32_16x16x32_bf16 v[40:43], v[158:161], v[236:239], v[40:43]
	v_mfma_f32_16x16x32_bf16 v[30:33], v[184:187], v[236:239], v[30:33]
	v_mfma_f32_16x16x32_bf16 v[22:25], v[158:161], v[244:247], v[22:25]
	v_mfma_f32_16x16x32_bf16 v[14:17], v[184:187], v[244:247], v[14:17]
	s_setprio 0
	s_setprio 1
	v_mfma_f32_16x16x32_bf16 v[52:55], v[188:191], v[162:165], v[52:55]
	v_mfma_f32_16x16x32_bf16 v[44:47], v[196:199], v[162:165], v[44:47]
	v_mfma_f32_16x16x32_bf16 v[36:39], v[188:191], v[224:227], v[36:39]
	v_mfma_f32_16x16x32_bf16 v[26:29], v[196:199], v[224:227], v[26:29]
	v_mfma_f32_16x16x32_bf16 v[18:21], v[188:191], v[232:235], v[18:21]
	v_mfma_f32_16x16x32_bf16 v[10:13], v[196:199], v[232:235], v[10:13]
	v_mfma_f32_16x16x32_bf16 v[6:9], v[188:191], v[240:243], v[6:9]
	v_mfma_f32_16x16x32_bf16 v[2:5], v[196:199], v[240:243], v[2:5]
	v_mfma_f32_16x16x32_bf16 v[52:55], v[192:195], v[204:207], v[52:55]
	v_mfma_f32_16x16x32_bf16 v[44:47], v[200:203], v[204:207], v[44:47]
	v_mfma_f32_16x16x32_bf16 v[36:39], v[192:195], v[228:231], v[36:39]
	v_mfma_f32_16x16x32_bf16 v[26:29], v[200:203], v[228:231], v[26:29]
	v_mfma_f32_16x16x32_bf16 v[18:21], v[192:195], v[236:239], v[18:21]
	v_mfma_f32_16x16x32_bf16 v[10:13], v[200:203], v[236:239], v[10:13]
	v_mfma_f32_16x16x32_bf16 v[6:9], v[192:195], v[244:247], v[6:9]
	v_mfma_f32_16x16x32_bf16 v[2:5], v[200:203], v[244:247], v[2:5]
	s_setprio 0
	s_barrier
	s_add_i32 s39, 0, 0x18000
	v_add_u32_e32 v34, s39, v151
	s_add_i32 s43, 0, 0x1c000
	ds_read_b128 v[144:147], v34
	ds_read_b128 v[158:161], v34 offset:1024
	ds_read_b128 v[162:165], v34 offset:2048
	ds_read_b128 v[180:183], v34 offset:3072
	v_add_u32_e32 v34, s43, v151
	ds_read_b128 v[184:187], v34
	ds_read_b128 v[188:191], v34 offset:1024
	ds_read_b128 v[192:195], v34 offset:2048
	ds_read_b128 v[196:199], v34 offset:3072
	s_add_u32 s36, s36, 0x80000
	s_addc_u32 s37, s37, 0
	s_mov_b32 m0, s54
	v_lshl_add_u64 v[168:169], s[36:37], 0, v[132:133]
	ds_read_b128 v[200:203], v157 offset:32768
	ds_read_b128 v[204:207], v157 offset:33792
	ds_read_b128 v[224:227], v157 offset:34816
	ds_read_b128 v[228:231], v157 offset:35840
	ds_read_b128 v[232:235], v157 offset:36864
	ds_read_b128 v[236:239], v157 offset:37888
	ds_read_b128 v[240:243], v157 offset:38912
	ds_read_b128 v[244:247], v157 offset:39936
	global_load_lds_dwordx4 v[168:169], off
	v_lshl_add_u64 v[168:169], s[36:37], 0, v[136:137]
	s_mov_b32 m0, s55
	s_nop 0
	global_load_lds_dwordx4 v[168:169], off
	s_waitcnt vmcnt(8)
	s_waitcnt lgkmcnt(0)
	s_barrier
	s_setprio 1
	s_waitcnt lgkmcnt(0)
	v_mfma_f32_16x16x32_bf16 v[128:131], v[144:147], v[200:203], v[128:131]
	v_mfma_f32_16x16x32_bf16 v[124:127], v[162:165], v[200:203], v[124:127]
	v_mfma_f32_16x16x32_bf16 v[120:123], v[144:147], v[224:227], v[120:123]
	v_mfma_f32_16x16x32_bf16 v[112:115], v[162:165], v[224:227], v[112:115]
	v_mfma_f32_16x16x32_bf16 v[104:107], v[144:147], v[232:235], v[104:107]
	v_mfma_f32_16x16x32_bf16 v[96:99], v[162:165], v[232:235], v[96:99]
	v_mfma_f32_16x16x32_bf16 v[88:91], v[144:147], v[240:243], v[88:91]
	v_mfma_f32_16x16x32_bf16 v[80:83], v[162:165], v[240:243], v[80:83]
	v_mfma_f32_16x16x32_bf16 v[128:131], v[158:161], v[204:207], v[128:131]
	v_mfma_f32_16x16x32_bf16 v[124:127], v[180:183], v[204:207], v[124:127]
	v_mfma_f32_16x16x32_bf16 v[120:123], v[158:161], v[228:231], v[120:123]
	v_mfma_f32_16x16x32_bf16 v[112:115], v[180:183], v[228:231], v[112:115]
	v_mfma_f32_16x16x32_bf16 v[104:107], v[158:161], v[236:239], v[104:107]
	v_mfma_f32_16x16x32_bf16 v[96:99], v[180:183], v[236:239], v[96:99]
	v_mfma_f32_16x16x32_bf16 v[88:91], v[158:161], v[244:247], v[88:91]
	v_mfma_f32_16x16x32_bf16 v[80:83], v[180:183], v[244:247], v[80:83]
	s_setprio 0
	s_setprio 1
	v_mfma_f32_16x16x32_bf16 v[116:119], v[184:187], v[200:203], v[116:119]
	v_mfma_f32_16x16x32_bf16 v[108:111], v[192:195], v[200:203], v[108:111]
	v_mfma_f32_16x16x32_bf16 v[100:103], v[184:187], v[224:227], v[100:103]
	v_mfma_f32_16x16x32_bf16 v[92:95], v[192:195], v[224:227], v[92:95]
	v_mfma_f32_16x16x32_bf16 v[84:87], v[184:187], v[232:235], v[84:87]
	v_mfma_f32_16x16x32_bf16 v[76:79], v[192:195], v[232:235], v[76:79]
	v_mfma_f32_16x16x32_bf16 v[72:75], v[184:187], v[240:243], v[72:75]
	v_mfma_f32_16x16x32_bf16 v[68:71], v[192:195], v[240:243], v[68:71]
	v_mfma_f32_16x16x32_bf16 v[116:119], v[188:191], v[204:207], v[116:119]
	v_mfma_f32_16x16x32_bf16 v[108:111], v[196:199], v[204:207], v[108:111]
	v_mfma_f32_16x16x32_bf16 v[100:103], v[188:191], v[228:231], v[100:103]
	v_mfma_f32_16x16x32_bf16 v[92:95], v[196:199], v[228:231], v[92:95]
	v_mfma_f32_16x16x32_bf16 v[84:87], v[188:191], v[236:239], v[84:87]
	v_mfma_f32_16x16x32_bf16 v[76:79], v[196:199], v[236:239], v[76:79]
	v_mfma_f32_16x16x32_bf16 v[72:75], v[188:191], v[244:247], v[72:75]
	v_mfma_f32_16x16x32_bf16 v[68:71], v[196:199], v[244:247], v[68:71]
	s_setprio 0
	s_barrier
; #define PG8_STAGE(bufoff, gbase, voff) do { _Pragma("unroll") for (int _i = 0; _i < 2; ++_i) \
;         __builtin_amdgcn_global_load_lds((const unsigned*)((const char*)(gbase) + (voff)[_i]), (LAS unsigned*)(lds + (bufoff) + ldsw + _i * 8192), 16, 0, 0); } while (0)
; #define PG8_LDA(dst, b, h) do { _Pragma("unroll") for (int m = 0; m < 4; ++m) _Pragma("unroll") for (int k = 0; k < 2; ++k) dst[m][k] = *(const LAS bf16x8*)(lds + PG8_SA(b, h) + aoff + m * 2048 + k * 1024); } while (0)
; #define PG8_MMA(ai, bj, At, Bt) do { __builtin_amdgcn_s_setprio(1); _Pragma("unroll") for (int m = 0; m < 4; ++m) _Pragma("unroll") for (int n = 0; n < 2; ++n) _Pragma("unroll") for (int k = 0; k < 2; ++k) \
;         acc[ai][bj][m][n] = __builtin_amdgcn_mfma_f32_16x16x32_bf16(Bt[n][k], At[m][k], acc[ai][bj][m][n], 0, 0, 0); __builtin_amdgcn_s_setprio(0); } while (0)
; #define PG8_WAIT_V(n) asm volatile("s_waitcnt vmcnt(" #n ")" ::: "memory")
; #define PG8_WAIT_L(n) asm volatile("s_waitcnt lgkmcnt(" #n ")" ::: "memory")
; #define PG8_BAR __builtin_amdgcn_s_barrier()
; #define PG8_SCHED __builtin_amdgcn_sched_barrier(0)
;     ...
;         for (int t = 0; t < nt; t += 2) {
;             const bool last = (t == nt - 2);
;             const char* a1 = cA + (size_t)(t + 1) * kstep;
;             const char* a2 = last ? nA : cA + (size_t)(t + 2) * kstep; const char* b2 = last ? nB : cB + (size_t)(t + 2) * kstep;
;             const char* a3 = a2 + kstep; const char* b3 = b2 + kstep;
;     ...
;             PG8_LDA(At, 1, 1); PG8_STAGE(PG8_SB(1, 0), b3, voffB); PG8_STAGE(PG8_SB(1, 1), b3 + hstep, voffB); PG8_STAGE(PG8_SA(1, 0), a3, voffA);
;             PG8_WAIT_V(8); PG8_WAIT_L(0); PG8_BAR; PG8_MMA(1, 0, At, B0); PG8_MMA(1, 1, At, B1); PG8_BAR; PG8_SCHED;
	s_add_i32 s36, s39, s51
	v_lshl_add_u64 v[148:149], v[148:149], 0, s[22:23]
	s_mov_b32 m0, s36
	ds_read_b128 v[200:203], v157 offset:49152
	ds_read_b128 v[204:207], v157 offset:50176
	ds_read_b128 v[224:227], v157 offset:51200
	ds_read_b128 v[228:231], v157 offset:52224
	ds_read_b128 v[232:235], v157 offset:53248
	ds_read_b128 v[236:239], v157 offset:54272
	ds_read_b128 v[240:243], v157 offset:55296
	ds_read_b128 v[244:247], v157 offset:56320
	global_load_lds_dwordx4 v[148:149], off
	s_add_i32 m0, s36, 0x2000
	s_add_u32 s34, s34, 0x80080
	v_lshl_add_u64 v[148:149], v[248:249], 0, s[22:23]
	s_addc_u32 s35, s35, 0
	s_add_i32 s36, s43, s51
	global_load_lds_dwordx4 v[148:149], off
	v_lshl_add_u64 v[148:149], s[34:35], 0, v[134:135]
	s_mov_b32 m0, s36
	s_nop 0
	global_load_lds_dwordx4 v[148:149], off
	v_lshl_add_u64 v[148:149], s[34:35], 0, v[138:139]
	s_add_i32 m0, s36, 0x2000
	s_nop 0
	global_load_lds_dwordx4 v[148:149], off
	v_lshl_add_u64 v[148:149], v[222:223], 0, s[22:23]
	s_mov_b32 m0, s20
	s_nop 0
	global_load_lds_dwordx4 v[148:149], off
	v_lshl_add_u64 v[148:149], v[166:167], 0, s[22:23]
	s_mov_b32 m0, s56
	s_nop 0
	global_load_lds_dwordx4 v[148:149], off
	s_waitcnt vmcnt(8)
	s_waitcnt lgkmcnt(0)
	s_barrier
	s_setprio 1
	s_waitcnt lgkmcnt(0)
	v_mfma_f32_16x16x32_bf16 v[64:67], v[144:147], v[200:203], v[64:67]
	v_mfma_f32_16x16x32_bf16 v[60:63], v[162:165], v[200:203], v[60:63]
	v_mfma_f32_16x16x32_bf16 v[56:59], v[144:147], v[224:227], v[56:59]
	v_mfma_f32_16x16x32_bf16 v[48:51], v[162:165], v[224:227], v[48:51]
	v_mfma_f32_16x16x32_bf16 v[40:43], v[144:147], v[232:235], v[40:43]
	v_mfma_f32_16x16x32_bf16 v[30:33], v[162:165], v[232:235], v[30:33]
	v_mfma_f32_16x16x32_bf16 v[22:25], v[144:147], v[240:243], v[22:25]
	v_mfma_f32_16x16x32_bf16 v[14:17], v[162:165], v[240:243], v[14:17]
	v_mfma_f32_16x16x32_bf16 v[64:67], v[158:161], v[204:207], v[64:67]
	v_mfma_f32_16x16x32_bf16 v[60:63], v[180:183], v[204:207], v[60:63]
	v_mfma_f32_16x16x32_bf16 v[56:59], v[158:161], v[228:231], v[56:59]
	v_mfma_f32_16x16x32_bf16 v[48:51], v[180:183], v[228:231], v[48:51]
	v_mfma_f32_16x16x32_bf16 v[40:43], v[158:161], v[236:239], v[40:43]
	v_mfma_f32_16x16x32_bf16 v[30:33], v[180:183], v[236:239], v[30:33]
	v_mfma_f32_16x16x32_bf16 v[22:25], v[158:161], v[244:247], v[22:25]
	v_mfma_f32_16x16x32_bf16 v[14:17], v[180:183], v[244:247], v[14:17]
	s_setprio 0
	s_setprio 1
	v_mfma_f32_16x16x32_bf16 v[52:55], v[184:187], v[200:203], v[52:55]
	v_mfma_f32_16x16x32_bf16 v[44:47], v[192:195], v[200:203], v[44:47]
	v_mfma_f32_16x16x32_bf16 v[36:39], v[184:187], v[224:227], v[36:39]
	v_mfma_f32_16x16x32_bf16 v[26:29], v[192:195], v[224:227], v[26:29]
	v_mfma_f32_16x16x32_bf16 v[18:21], v[184:187], v[232:235], v[18:21]
	v_mfma_f32_16x16x32_bf16 v[10:13], v[192:195], v[232:235], v[10:13]
	v_mfma_f32_16x16x32_bf16 v[6:9], v[184:187], v[240:243], v[6:9]
	v_mfma_f32_16x16x32_bf16 v[2:5], v[192:195], v[240:243], v[2:5]
	v_mfma_f32_16x16x32_bf16 v[52:55], v[188:191], v[204:207], v[52:55]
	v_mfma_f32_16x16x32_bf16 v[44:47], v[196:199], v[204:207], v[44:47]
	v_mfma_f32_16x16x32_bf16 v[36:39], v[188:191], v[228:231], v[36:39]
	v_mfma_f32_16x16x32_bf16 v[26:29], v[196:199], v[228:231], v[26:29]
	v_mfma_f32_16x16x32_bf16 v[18:21], v[188:191], v[236:239], v[18:21]
	v_mfma_f32_16x16x32_bf16 v[10:13], v[196:199], v[236:239], v[10:13]
	v_mfma_f32_16x16x32_bf16 v[6:9], v[188:191], v[244:247], v[6:9]
	v_mfma_f32_16x16x32_bf16 v[2:5], v[196:199], v[244:247], v[2:5]
	s_setprio 0
	s_add_i32 s38, s38, 2
	s_add_u32 s26, s26, 0x100
	s_addc_u32 s27, s27, 0
	s_add_u32 s31, s31, 0x100
	s_addc_u32 s33, s33, 0
	s_add_u32 s34, s26, 0xfff80080
	s_addc_u32 s35, s27, -1
	s_add_i32 s39, 0, 0x10000
	s_cmp_eq_u32 s38, 28
	s_cselect_b32 s37, s3, s35
	s_cselect_b32 s36, s5, s34
	s_cselect_b32 s35, s28, s33
	s_cselect_b32 s34, s30, s31
	s_add_i32 s43, 0, 0x14000
	s_cmp_gt_u32 s38, 29
	s_barrier
	s_cbranch_scc0 .Lkrot_0
	s_and_b64 vcc, exec, s[40:41]
	s_cbranch_vccz .LBB0_132
	s_barrier

; #define PG8_STAGE(bufoff, gbase, voff) do { _Pragma("unroll") for (int _i = 0; _i < 2; ++_i) \
;         __builtin_amdgcn_global_load_lds((const unsigned*)((const char*)(gbase) + (voff)[_i]), (LAS unsigned*)(lds + (bufoff) + ldsw + _i * 8192), 16, 0, 0); } while (0)
; #define PG8_LDA(dst, b, h) do { _Pragma("unroll") for (int m = 0; m < 4; ++m) _Pragma("unroll") for (int k = 0; k < 2; ++k) dst[m][k] = *(const LAS bf16x8*)(lds + PG8_SA(b, h) + aoff + m * 2048 + k * 1024); } while (0)
; #define PG8_LDB(dst, b, h) do { _Pragma("unroll") for (int n = 0; n < 2; ++n) _Pragma("unroll") for (int k = 0; k < 2; ++k) dst[n][k] = *(const LAS bf16x8*)(lds + PG8_SB(b, h) + boff + n * 2048 + k * 1024); } while (0)
; #define PG8_MMA(ai, bj, At, Bt) do { __builtin_amdgcn_s_setprio(1); _Pragma("unroll") for (int m = 0; m < 4; ++m) _Pragma("unroll") for (int n = 0; n < 2; ++n) _Pragma("unroll") for (int k = 0; k < 2; ++k) \
;         acc[ai][bj][m][n] = __builtin_amdgcn_mfma_f32_16x16x32_bf16(Bt[n][k], At[m][k], acc[ai][bj][m][n], 0, 0, 0); __builtin_amdgcn_s_setprio(0); } while (0)
; #define PG8_WAIT_V(n) asm volatile("s_waitcnt vmcnt(" #n ")" ::: "memory")
; #define PG8_WAIT_L(n) asm volatile("s_waitcnt lgkmcnt(" #n ")" ::: "memory")
; #define PG8_BAR __builtin_amdgcn_s_barrier()
; #define PG8_SCHED __builtin_amdgcn_sched_barrier(0)
;     ...
;             PG8_LDB(B0, 0, 0); PG8_LDB(B1, 0, 1); PG8_SCHED; PG8_LDA(At, 0, 0); PG8_STAGE(PG8_SA(1, 1), a1 + hstep, voffA);
;             PG8_WAIT_V(8); PG8_WAIT_L(0); PG8_BAR; PG8_MMA(0, 0, At, B0); PG8_MMA(0, 1, At, B1); PG8_BAR; PG8_SCHED;
;             PG8_LDA(At, 0, 1); PG8_STAGE(PG8_SB(0, 0), b2, voffB); PG8_STAGE(PG8_SB(0, 1), b2 + hstep, voffB); PG8_STAGE(PG8_SA(0, 0), a2, voffA);
.Lkrot_1:
	v_add_u32_e32 v144, s51, v207
	v_add_u32_e32 v160, s62, v207
	ds_read_b128 v[132:135], v144
	ds_read_b128 v[136:139], v144 offset:1024
	ds_read_b128 v[140:143], v144 offset:2048
	ds_read_b128 v[144:147], v144 offset:3072
	ds_read_b128 v[148:151], v160
	ds_read_b128 v[152:155], v160 offset:1024
	ds_read_b128 v[156:159], v160 offset:2048
	ds_read_b128 v[160:163], v160 offset:3072
	v_lshl_add_u64 v[164:165], s[2:3], 0, v[186:187]
	s_add_i32 m0, s29, 0xc000
	ds_read_b128 v[190:193], v225
	ds_read_b128 v[194:197], v225 offset:1024
	ds_read_b128 v[198:201], v225 offset:2048
	ds_read_b128 v[202:205], v225 offset:3072
	ds_read_b128 v[226:229], v225 offset:4096
	ds_read_b128 v[230:233], v225 offset:5120
	ds_read_b128 v[234:237], v225 offset:6144
	ds_read_b128 v[238:241], v225 offset:7168
	global_load_lds_dwordx4 v[164:165], off
	v_lshl_add_u64 v[164:165], s[2:3], 0, v[188:189]
	s_add_i32 m0, s29, 0xe000
	s_nop 0
	global_load_lds_dwordx4 v[164:165], off
	s_waitcnt vmcnt(8)
	s_waitcnt lgkmcnt(0)
	s_barrier
	s_setprio 1
	s_waitcnt lgkmcnt(0)
	v_mfma_f32_16x16x32_bf16 v[124:127], v[132:135], v[190:193], v[124:127]
	v_mfma_f32_16x16x32_bf16 v[128:131], v[140:143], v[190:193], v[128:131]
	v_mfma_f32_16x16x32_bf16 v[108:111], v[132:135], v[198:201], v[108:111]
	v_mfma_f32_16x16x32_bf16 v[112:115], v[140:143], v[198:201], v[112:115]
	v_mfma_f32_16x16x32_bf16 v[92:95], v[132:135], v[226:229], v[92:95]
	v_mfma_f32_16x16x32_bf16 v[96:99], v[140:143], v[226:229], v[96:99]
	v_mfma_f32_16x16x32_bf16 v[76:79], v[132:135], v[234:237], v[76:79]
	v_mfma_f32_16x16x32_bf16 v[80:83], v[140:143], v[234:237], v[80:83]
	v_mfma_f32_16x16x32_bf16 v[124:127], v[136:139], v[194:197], v[124:127]
	v_mfma_f32_16x16x32_bf16 v[128:131], v[144:147], v[194:197], v[128:131]
	v_mfma_f32_16x16x32_bf16 v[108:111], v[136:139], v[202:205], v[108:111]
	v_mfma_f32_16x16x32_bf16 v[112:115], v[144:147], v[202:205], v[112:115]
	v_mfma_f32_16x16x32_bf16 v[92:95], v[136:139], v[230:233], v[92:95]
	v_mfma_f32_16x16x32_bf16 v[96:99], v[144:147], v[230:233], v[96:99]
	v_mfma_f32_16x16x32_bf16 v[76:79], v[136:139], v[238:241], v[76:79]
	v_mfma_f32_16x16x32_bf16 v[80:83], v[144:147], v[238:241], v[80:83]
	s_setprio 0
	s_setprio 1
	v_mfma_f32_16x16x32_bf16 v[120:123], v[148:151], v[190:193], v[120:123]
	v_mfma_f32_16x16x32_bf16 v[116:119], v[156:159], v[190:193], v[116:119]
	v_mfma_f32_16x16x32_bf16 v[104:107], v[148:151], v[198:201], v[104:107]
	v_mfma_f32_16x16x32_bf16 v[100:103], v[156:159], v[198:201], v[100:103]
	v_mfma_f32_16x16x32_bf16 v[88:91], v[148:151], v[226:229], v[88:91]
	v_mfma_f32_16x16x32_bf16 v[84:87], v[156:159], v[226:229], v[84:87]
	v_mfma_f32_16x16x32_bf16 v[72:75], v[148:151], v[234:237], v[72:75]
	v_mfma_f32_16x16x32_bf16 v[68:71], v[156:159], v[234:237], v[68:71]
	v_mfma_f32_16x16x32_bf16 v[120:123], v[152:155], v[194:197], v[120:123]
	v_mfma_f32_16x16x32_bf16 v[116:119], v[160:163], v[194:197], v[116:119]
	v_mfma_f32_16x16x32_bf16 v[104:107], v[152:155], v[202:205], v[104:107]
	v_mfma_f32_16x16x32_bf16 v[100:103], v[160:163], v[202:205], v[100:103]
	v_mfma_f32_16x16x32_bf16 v[88:91], v[152:155], v[230:233], v[88:91]
	v_mfma_f32_16x16x32_bf16 v[84:87], v[160:163], v[230:233], v[84:87]
	v_mfma_f32_16x16x32_bf16 v[72:75], v[152:155], v[238:241], v[72:75]
	v_mfma_f32_16x16x32_bf16 v[68:71], v[160:163], v[238:241], v[68:71]
	s_setprio 0
	s_barrier
	s_add_i32 s51, s51, s25
	v_lshl_add_u64 v[164:165], s[26:27], 0, v[34:35]
	s_mov_b32 m0, s51
	ds_read_b128 v[190:193], v225 offset:16384
	ds_read_b128 v[194:197], v225 offset:17408
	ds_read_b128 v[198:201], v225 offset:18432
	ds_read_b128 v[202:205], v225 offset:19456
	ds_read_b128 v[226:229], v225 offset:20480
	ds_read_b128 v[230:233], v225 offset:21504
	ds_read_b128 v[234:237], v225 offset:22528
	ds_read_b128 v[238:241], v225 offset:23552
	global_load_lds_dwordx4 v[164:165], off
	s_add_i32 m0, s51, 0x2000
	s_add_u32 s60, s26, 0x80000
	v_lshl_add_u64 v[166:167], s[26:27], 0, v[180:181]
	s_addc_u32 s61, s27, 0
	s_add_i32 s51, s62, s25
	global_load_lds_dwordx4 v[166:167], off
	v_lshl_add_u64 v[168:169], s[60:61], 0, v[34:35]
	s_mov_b32 m0, s51
	v_lshl_add_u64 v[222:223], s[34:35], 0, v[182:183]
	global_load_lds_dwordx4 v[168:169], off
	v_lshl_add_u64 v[168:169], s[60:61], 0, v[180:181]
	s_add_i32 m0, s51, 0x2000
	s_nop 0
	global_load_lds_dwordx4 v[168:169], off
	v_lshl_add_u64 v[168:169], s[34:35], 0, v[184:185]
	s_mov_b32 m0, s29
	s_nop 0
	global_load_lds_dwordx4 v[168:169], off
	s_mov_b32 m0, s36
	s_nop 0
	global_load_lds_dwordx4 v[222:223], off
	s_waitcnt vmcnt(8)
	s_waitcnt lgkmcnt(0)
	s_barrier
; #define PG8_STAGE(bufoff, gbase, voff) do { _Pragma("unroll") for (int _i = 0; _i < 2; ++_i) \
;         __builtin_amdgcn_global_load_lds((const unsigned*)((const char*)(gbase) + (voff)[_i]), (LAS unsigned*)(lds + (bufoff) + ldsw + _i * 8192), 16, 0, 0); } while (0)
; #define PG8_LDA(dst, b, h) do { _Pragma("unroll") for (int m = 0; m < 4; ++m) _Pragma("unroll") for (int k = 0; k < 2; ++k) dst[m][k] = *(const LAS bf16x8*)(lds + PG8_SA(b, h) + aoff + m * 2048 + k * 1024); } while (0)
; #define PG8_LDB(dst, b, h) do { _Pragma("unroll") for (int n = 0; n < 2; ++n) _Pragma("unroll") for (int k = 0; k < 2; ++k) dst[n][k] = *(const LAS bf16x8*)(lds + PG8_SB(b, h) + boff + n * 2048 + k * 1024); } while (0)
; #define PG8_MMA(ai, bj, At, Bt) do { __builtin_amdgcn_s_setprio(1); _Pragma("unroll") for (int m = 0; m < 4; ++m) _Pragma("unroll") for (int n = 0; n < 2; ++n) _Pragma("unroll") for (int k = 0; k < 2; ++k) \
;         acc[ai][bj][m][n] = __builtin_amdgcn_mfma_f32_16x16x32_bf16(Bt[n][k], At[m][k], acc[ai][bj][m][n], 0, 0, 0); __builtin_amdgcn_s_setprio(0); } while (0)
; #define PG8_WAIT_V(n) asm volatile("s_waitcnt vmcnt(" #n ")" ::: "memory")
; #define PG8_WAIT_L(n) asm volatile("s_waitcnt lgkmcnt(" #n ")" ::: "memory")
; #define PG8_BAR __builtin_amdgcn_s_barrier()
; #define PG8_SCHED __builtin_amdgcn_sched_barrier(0)
;     ...
;             PG8_WAIT_V(8); PG8_WAIT_L(0); PG8_BAR; PG8_MMA(1, 0, At, B0); PG8_MMA(1, 1, At, B1); PG8_BAR; PG8_SCHED;
;             PG8_LDB(B0, 1, 0); PG8_LDB(B1, 1, 1); PG8_SCHED; PG8_LDA(At, 1, 0); PG8_STAGE(PG8_SA(0, 1), a2 + hstep, voffA);
;             PG8_WAIT_V(8); PG8_WAIT_L(0); PG8_BAR; PG8_MMA(0, 0, At, B0); PG8_MMA(0, 1, At, B1); PG8_BAR; PG8_SCHED;
	s_setprio 1
	s_waitcnt lgkmcnt(0)
	v_mfma_f32_16x16x32_bf16 v[60:63], v[132:135], v[190:193], v[60:63]
	v_mfma_f32_16x16x32_bf16 v[64:67], v[140:143], v[190:193], v[64:67]
	v_mfma_f32_16x16x32_bf16 v[44:47], v[132:135], v[198:201], v[44:47]
	v_mfma_f32_16x16x32_bf16 v[48:51], v[140:143], v[198:201], v[48:51]
	v_mfma_f32_16x16x32_bf16 v[26:29], v[132:135], v[226:229], v[26:29]
	v_mfma_f32_16x16x32_bf16 v[30:33], v[140:143], v[226:229], v[30:33]
	v_mfma_f32_16x16x32_bf16 v[10:13], v[132:135], v[234:237], v[10:13]
	v_mfma_f32_16x16x32_bf16 v[14:17], v[140:143], v[234:237], v[14:17]
	v_mfma_f32_16x16x32_bf16 v[60:63], v[136:139], v[194:197], v[60:63]
	v_mfma_f32_16x16x32_bf16 v[64:67], v[144:147], v[194:197], v[64:67]
	v_mfma_f32_16x16x32_bf16 v[44:47], v[136:139], v[202:205], v[44:47]
	v_mfma_f32_16x16x32_bf16 v[48:51], v[144:147], v[202:205], v[48:51]
	v_mfma_f32_16x16x32_bf16 v[26:29], v[136:139], v[230:233], v[26:29]
	v_mfma_f32_16x16x32_bf16 v[30:33], v[144:147], v[230:233], v[30:33]
	v_mfma_f32_16x16x32_bf16 v[10:13], v[136:139], v[238:241], v[10:13]
	v_mfma_f32_16x16x32_bf16 v[14:17], v[144:147], v[238:241], v[14:17]
	s_setprio 0
	s_setprio 1
	v_mfma_f32_16x16x32_bf16 v[56:59], v[148:151], v[190:193], v[56:59]
	v_mfma_f32_16x16x32_bf16 v[52:55], v[156:159], v[190:193], v[52:55]
	v_mfma_f32_16x16x32_bf16 v[40:43], v[148:151], v[198:201], v[40:43]
	v_mfma_f32_16x16x32_bf16 v[36:39], v[156:159], v[198:201], v[36:39]
	v_mfma_f32_16x16x32_bf16 v[22:25], v[148:151], v[226:229], v[22:25]
	v_mfma_f32_16x16x32_bf16 v[18:21], v[156:159], v[226:229], v[18:21]
	v_mfma_f32_16x16x32_bf16 v[6:9], v[148:151], v[234:237], v[6:9]
	v_mfma_f32_16x16x32_bf16 v[2:5], v[156:159], v[234:237], v[2:5]
	v_mfma_f32_16x16x32_bf16 v[56:59], v[152:155], v[194:197], v[56:59]
	v_mfma_f32_16x16x32_bf16 v[52:55], v[160:163], v[194:197], v[52:55]
	v_mfma_f32_16x16x32_bf16 v[40:43], v[152:155], v[202:205], v[40:43]
	v_mfma_f32_16x16x32_bf16 v[36:39], v[160:163], v[202:205], v[36:39]
	v_mfma_f32_16x16x32_bf16 v[22:25], v[152:155], v[230:233], v[22:25]
	v_mfma_f32_16x16x32_bf16 v[18:21], v[160:163], v[230:233], v[18:21]
	v_mfma_f32_16x16x32_bf16 v[6:9], v[152:155], v[238:241], v[6:9]
	v_mfma_f32_16x16x32_bf16 v[2:5], v[160:163], v[238:241], v[2:5]
	s_setprio 0
	s_barrier
	s_add_i32 s51, 0, 0x18000
	s_add_i32 s60, 0, 0x1c000
	v_add_u32_e32 v144, s51, v207
	v_add_u32_e32 v160, s60, v207
	ds_read_b128 v[132:135], v144
	ds_read_b128 v[136:139], v144 offset:1024
	ds_read_b128 v[140:143], v144 offset:2048
	ds_read_b128 v[144:147], v144 offset:3072
	ds_read_b128 v[148:151], v160
	ds_read_b128 v[152:155], v160 offset:1024
	ds_read_b128 v[156:159], v160 offset:2048
	ds_read_b128 v[160:163], v160 offset:3072
	s_add_u32 s34, s34, 0x80000
	s_addc_u32 s35, s35, 0
	s_mov_b32 m0, s37
	v_lshl_add_u64 v[242:243], s[34:35], 0, v[184:185]
	ds_read_b128 v[190:193], v225 offset:32768
	ds_read_b128 v[194:197], v225 offset:33792
	ds_read_b128 v[198:201], v225 offset:34816
	ds_read_b128 v[202:205], v225 offset:35840
	ds_read_b128 v[226:229], v225 offset:36864
	ds_read_b128 v[230:233], v225 offset:37888
	ds_read_b128 v[234:237], v225 offset:38912
	ds_read_b128 v[238:241], v225 offset:39936
	global_load_lds_dwordx4 v[242:243], off
	v_lshl_add_u64 v[242:243], s[34:35], 0, v[182:183]
	s_mov_b32 m0, s56
	s_nop 0
	global_load_lds_dwordx4 v[242:243], off
	s_waitcnt vmcnt(8)
	s_waitcnt lgkmcnt(0)
	s_barrier
	s_setprio 1
	s_waitcnt lgkmcnt(0)
	v_mfma_f32_16x16x32_bf16 v[124:127], v[132:135], v[190:193], v[124:127]
	v_mfma_f32_16x16x32_bf16 v[128:131], v[140:143], v[190:193], v[128:131]
	v_mfma_f32_16x16x32_bf16 v[108:111], v[132:135], v[198:201], v[108:111]
	v_mfma_f32_16x16x32_bf16 v[112:115], v[140:143], v[198:201], v[112:115]
	v_mfma_f32_16x16x32_bf16 v[92:95], v[132:135], v[226:229], v[92:95]
	v_mfma_f32_16x16x32_bf16 v[96:99], v[140:143], v[226:229], v[96:99]
	v_mfma_f32_16x16x32_bf16 v[76:79], v[132:135], v[234:237], v[76:79]
	v_mfma_f32_16x16x32_bf16 v[80:83], v[140:143], v[234:237], v[80:83]
	v_mfma_f32_16x16x32_bf16 v[124:127], v[136:139], v[194:197], v[124:127]
	v_mfma_f32_16x16x32_bf16 v[128:131], v[144:147], v[194:197], v[128:131]
	v_mfma_f32_16x16x32_bf16 v[108:111], v[136:139], v[202:205], v[108:111]
	v_mfma_f32_16x16x32_bf16 v[112:115], v[144:147], v[202:205], v[112:115]
	v_mfma_f32_16x16x32_bf16 v[92:95], v[136:139], v[230:233], v[92:95]
	v_mfma_f32_16x16x32_bf16 v[96:99], v[144:147], v[230:233], v[96:99]
	v_mfma_f32_16x16x32_bf16 v[76:79], v[136:139], v[238:241], v[76:79]
	v_mfma_f32_16x16x32_bf16 v[80:83], v[144:147], v[238:241], v[80:83]
	s_setprio 0
	s_setprio 1
	v_mfma_f32_16x16x32_bf16 v[120:123], v[148:151], v[190:193], v[120:123]
	v_mfma_f32_16x16x32_bf16 v[116:119], v[156:159], v[190:193], v[116:119]
	v_mfma_f32_16x16x32_bf16 v[104:107], v[148:151], v[198:201], v[104:107]
	v_mfma_f32_16x16x32_bf16 v[100:103], v[156:159], v[198:201], v[100:103]
	v_mfma_f32_16x16x32_bf16 v[88:91], v[148:151], v[226:229], v[88:91]
	v_mfma_f32_16x16x32_bf16 v[84:87], v[156:159], v[226:229], v[84:87]
	v_mfma_f32_16x16x32_bf16 v[72:75], v[148:151], v[234:237], v[72:75]
	v_mfma_f32_16x16x32_bf16 v[68:71], v[156:159], v[234:237], v[68:71]
	v_mfma_f32_16x16x32_bf16 v[120:123], v[152:155], v[194:197], v[120:123]
	v_mfma_f32_16x16x32_bf16 v[116:119], v[160:163], v[194:197], v[116:119]
	v_mfma_f32_16x16x32_bf16 v[104:107], v[152:155], v[202:205], v[104:107]
	v_mfma_f32_16x16x32_bf16 v[100:103], v[160:163], v[202:205], v[100:103]
	v_mfma_f32_16x16x32_bf16 v[88:91], v[152:155], v[230:233], v[88:91]
	v_mfma_f32_16x16x32_bf16 v[84:87], v[160:163], v[230:233], v[84:87]
	v_mfma_f32_16x16x32_bf16 v[72:75], v[152:155], v[238:241], v[72:75]
	v_mfma_f32_16x16x32_bf16 v[68:71], v[160:163], v[238:241], v[68:71]
	s_setprio 0
	s_barrier
; #define PG8_STAGE(bufoff, gbase, voff) do { _Pragma("unroll") for (int _i = 0; _i < 2; ++_i) \
;         __builtin_amdgcn_global_load_lds((const unsigned*)((const char*)(gbase) + (voff)[_i]), (LAS unsigned*)(lds + (bufoff) + ldsw + _i * 8192), 16, 0, 0); } while (0)
; #define PG8_LDA(dst, b, h) do { _Pragma("unroll") for (int m = 0; m < 4; ++m) _Pragma("unroll") for (int k = 0; k < 2; ++k) dst[m][k] = *(const LAS bf16x8*)(lds + PG8_SA(b, h) + aoff + m * 2048 + k * 1024); } while (0)
; #define PG8_MMA(ai, bj, At, Bt) do { __builtin_amdgcn_s_setprio(1); _Pragma("unroll") for (int m = 0; m < 4; ++m) _Pragma("unroll") for (int n = 0; n < 2; ++n) _Pragma("unroll") for (int k = 0; k < 2; ++k) \
;         acc[ai][bj][m][n] = __builtin_amdgcn_mfma_f32_16x16x32_bf16(Bt[n][k], At[m][k], acc[ai][bj][m][n], 0, 0, 0); __builtin_amdgcn_s_setprio(0); } while (0)
; #define PG8_WAIT_V(n) asm volatile("s_waitcnt vmcnt(" #n ")" ::: "memory")
; #define PG8_WAIT_L(n) asm volatile("s_waitcnt lgkmcnt(" #n ")" ::: "memory")
; #define PG8_BAR __builtin_amdgcn_s_barrier()
; #define PG8_SCHED __builtin_amdgcn_sched_barrier(0)
;     ...
;         for (int t = 0; t < nt; t += 2) {
;             const bool last = (t == nt - 2);
;             const char* a1 = cA + (size_t)(t + 1) * kstep;
;             const char* a2 = last ? nA : cA + (size_t)(t + 2) * kstep; const char* b2 = last ? nB : cB + (size_t)(t + 2) * kstep;
;             const char* a3 = a2 + kstep; const char* b3 = b2 + kstep;
;     ...
;             PG8_LDA(At, 1, 1); PG8_STAGE(PG8_SB(1, 0), b3, voffB); PG8_STAGE(PG8_SB(1, 1), b3 + hstep, voffB); PG8_STAGE(PG8_SA(1, 0), a3, voffA);
;             PG8_WAIT_V(8); PG8_WAIT_L(0); PG8_BAR; PG8_MMA(1, 0, At, B0); PG8_MMA(1, 1, At, B1); PG8_BAR; PG8_SCHED;
	s_add_i32 s34, s51, s25
	v_lshl_add_u64 v[164:165], v[164:165], 0, s[22:23]
	s_mov_b32 m0, s34
	ds_read_b128 v[190:193], v225 offset:49152
	ds_read_b128 v[194:197], v225 offset:50176
	ds_read_b128 v[198:201], v225 offset:51200
	ds_read_b128 v[202:205], v225 offset:52224
	ds_read_b128 v[226:229], v225 offset:53248
	ds_read_b128 v[230:233], v225 offset:54272
	ds_read_b128 v[234:237], v225 offset:55296
	ds_read_b128 v[238:241], v225 offset:56320
	global_load_lds_dwordx4 v[164:165], off
	s_add_i32 m0, s34, 0x2000
	s_add_u32 s26, s26, 0x80080
	v_lshl_add_u64 v[164:165], v[166:167], 0, s[22:23]
	s_addc_u32 s27, s27, 0
	s_add_i32 s34, s60, s25
	global_load_lds_dwordx4 v[164:165], off
	v_lshl_add_u64 v[164:165], s[26:27], 0, v[34:35]
	s_mov_b32 m0, s34
	s_nop 0
	global_load_lds_dwordx4 v[164:165], off
	v_lshl_add_u64 v[164:165], s[26:27], 0, v[180:181]
	s_add_i32 m0, s34, 0x2000
	s_nop 0
	global_load_lds_dwordx4 v[164:165], off
	v_lshl_add_u64 v[164:165], v[168:169], 0, s[22:23]
	s_mov_b32 m0, s57
	s_nop 0
	global_load_lds_dwordx4 v[164:165], off
	v_lshl_add_u64 v[164:165], v[222:223], 0, s[22:23]
	s_mov_b32 m0, s58
	s_nop 0
	global_load_lds_dwordx4 v[164:165], off
	s_waitcnt vmcnt(8)
	s_waitcnt lgkmcnt(0)
	s_barrier
	s_setprio 1
	s_waitcnt lgkmcnt(0)
	v_mfma_f32_16x16x32_bf16 v[60:63], v[132:135], v[190:193], v[60:63]
	v_mfma_f32_16x16x32_bf16 v[64:67], v[140:143], v[190:193], v[64:67]
	v_mfma_f32_16x16x32_bf16 v[44:47], v[132:135], v[198:201], v[44:47]
	v_mfma_f32_16x16x32_bf16 v[48:51], v[140:143], v[198:201], v[48:51]
	v_mfma_f32_16x16x32_bf16 v[26:29], v[132:135], v[226:229], v[26:29]
	v_mfma_f32_16x16x32_bf16 v[30:33], v[140:143], v[226:229], v[30:33]
	v_mfma_f32_16x16x32_bf16 v[10:13], v[132:135], v[234:237], v[10:13]
	v_mfma_f32_16x16x32_bf16 v[14:17], v[140:143], v[234:237], v[14:17]
	v_mfma_f32_16x16x32_bf16 v[60:63], v[136:139], v[194:197], v[60:63]
	v_mfma_f32_16x16x32_bf16 v[64:67], v[144:147], v[194:197], v[64:67]
	v_mfma_f32_16x16x32_bf16 v[44:47], v[136:139], v[202:205], v[44:47]
	v_mfma_f32_16x16x32_bf16 v[48:51], v[144:147], v[202:205], v[48:51]
	v_mfma_f32_16x16x32_bf16 v[26:29], v[136:139], v[230:233], v[26:29]
	v_mfma_f32_16x16x32_bf16 v[30:33], v[144:147], v[230:233], v[30:33]
	v_mfma_f32_16x16x32_bf16 v[10:13], v[136:139], v[238:241], v[10:13]
	v_mfma_f32_16x16x32_bf16 v[14:17], v[144:147], v[238:241], v[14:17]
	s_setprio 0
	s_setprio 1
	v_mfma_f32_16x16x32_bf16 v[56:59], v[148:151], v[190:193], v[56:59]
	v_mfma_f32_16x16x32_bf16 v[52:55], v[156:159], v[190:193], v[52:55]
	v_mfma_f32_16x16x32_bf16 v[40:43], v[148:151], v[198:201], v[40:43]
	v_mfma_f32_16x16x32_bf16 v[36:39], v[156:159], v[198:201], v[36:39]
	v_mfma_f32_16x16x32_bf16 v[22:25], v[148:151], v[226:229], v[22:25]
	v_mfma_f32_16x16x32_bf16 v[18:21], v[156:159], v[226:229], v[18:21]
	v_mfma_f32_16x16x32_bf16 v[6:9], v[148:151], v[234:237], v[6:9]
	v_mfma_f32_16x16x32_bf16 v[2:5], v[156:159], v[234:237], v[2:5]
	v_mfma_f32_16x16x32_bf16 v[56:59], v[152:155], v[194:197], v[56:59]
	v_mfma_f32_16x16x32_bf16 v[52:55], v[160:163], v[194:197], v[52:55]
	v_mfma_f32_16x16x32_bf16 v[40:43], v[152:155], v[202:205], v[40:43]
	v_mfma_f32_16x16x32_bf16 v[36:39], v[160:163], v[202:205], v[36:39]
	v_mfma_f32_16x16x32_bf16 v[22:25], v[152:155], v[230:233], v[22:25]
	v_mfma_f32_16x16x32_bf16 v[18:21], v[160:163], v[230:233], v[18:21]
	v_mfma_f32_16x16x32_bf16 v[6:9], v[152:155], v[238:241], v[6:9]
	v_mfma_f32_16x16x32_bf16 v[2:5], v[160:163], v[238:241], v[2:5]
	s_setprio 0
	s_add_i32 s49, s49, 2
	s_add_u32 s2, s2, 0x100
	s_addc_u32 s3, s3, 0
	s_add_u32 s46, s46, 0x100
	s_addc_u32 s47, s47, 0
	s_add_u32 s26, s2, 0xfff80080
	s_addc_u32 s27, s3, -1
	s_add_i32 s51, 0, 0x10000
	s_cmp_eq_u32 s49, 28
	s_cselect_b32 s35, s31, s27
	s_cselect_b32 s34, s33, s26
	s_cselect_b32 s27, s44, s47
	s_cselect_b32 s26, s45, s46
	s_add_i32 s62, 0, 0x14000
	s_cmp_gt_u32 s49, 29
	s_barrier
	s_cbranch_scc0 .Lkrot_1
	s_and_b64 vcc, exec, s[18:19]
	s_cbranch_vccz .LBB0_1481
	s_barrier

; #define PG8_STAGE(bufoff, gbase, voff) do { _Pragma("unroll") for (int _i = 0; _i < 2; ++_i) \
;         __builtin_amdgcn_global_load_lds((const unsigned*)((const char*)(gbase) + (voff)[_i]), (LAS unsigned*)(lds + (bufoff) + ldsw + _i * 8192), 16, 0, 0); } while (0)
; #define PG8_LDA(dst, b, h) do { _Pragma("unroll") for (int m = 0; m < 4; ++m) _Pragma("unroll") for (int k = 0; k < 2; ++k) dst[m][k] = *(const LAS bf16x8*)(lds + PG8_SA(b, h) + aoff + m * 2048 + k * 1024); } while (0)
; #define PG8_LDB(dst, b, h) do { _Pragma("unroll") for (int n = 0; n < 2; ++n) _Pragma("unroll") for (int k = 0; k < 2; ++k) dst[n][k] = *(const LAS bf16x8*)(lds + PG8_SB(b, h) + boff + n * 2048 + k * 1024); } while (0)
; #define PG8_MMA(ai, bj, At, Bt) do { __builtin_amdgcn_s_setprio(1); _Pragma("unroll") for (int m = 0; m < 4; ++m) _Pragma("unroll") for (int n = 0; n < 2; ++n) _Pragma("unroll") for (int k = 0; k < 2; ++k) \
;         acc[ai][bj][m][n] = __builtin_amdgcn_mfma_f32_16x16x32_bf16(Bt[n][k], At[m][k], acc[ai][bj][m][n], 0, 0, 0); __builtin_amdgcn_s_setprio(0); } while (0)
; #define PG8_WAIT_V(n) asm volatile("s_waitcnt vmcnt(" #n ")" ::: "memory")
; #define PG8_WAIT_L(n) asm volatile("s_waitcnt lgkmcnt(" #n ")" ::: "memory")
; #define PG8_BAR __builtin_amdgcn_s_barrier()
; #define PG8_SCHED __builtin_amdgcn_sched_barrier(0)
;     ...
;         for (int t = 0; t < nt; t += 2) {
;             const bool last = (t == nt - 2);
;             const char* a1 = cA + (size_t)(t + 1) * kstep;
;             const char* a2 = last ? nA : cA + (size_t)(t + 2) * kstep; const char* b2 = last ? nB : cB + (size_t)(t + 2) * kstep;
;             const char* a3 = a2 + kstep; const char* b3 = b2 + kstep;
;             if constexpr (NB == 2) {
;             PG8_LDB(B0, 0, 0); PG8_LDB(B1, 0, 1); PG8_SCHED; PG8_LDA(At, 0, 0); PG8_STAGE(PG8_SA(1, 1), a1 + hstep, voffA);
;             PG8_WAIT_V(8); PG8_WAIT_L(0); PG8_BAR; PG8_MMA(0, 0, At, B0); PG8_MMA(0, 1, At, B1); PG8_BAR; PG8_SCHED;
;             PG8_LDA(At, 0, 1); PG8_STAGE(PG8_SB(0, 0), b2, voffB); PG8_STAGE(PG8_SB(0, 1), b2 + hstep, voffB); PG8_STAGE(PG8_SA(0, 0), a2, voffA);
.LBB0_1605:
	s_add_u32 s4, s2, 0xfff80080
	s_addc_u32 s5, s3, -1
	s_add_i32 s51, 0, 0x10000
	s_cmp_eq_u32 s50, 28
	s_cselect_b32 s27, s19, s5
	s_cselect_b32 s26, s31, s4
	s_cselect_b32 s5, s17, s49
	s_cselect_b32 s4, s33, s48
	s_add_i32 s54, 0, 0x14000
.Lkrot_2:
	v_add_u32_e32 v149, s51, v146
	ds_read_b128 v[142:145], v149
	ds_read_b128 v[150:153], v149 offset:1024
	ds_read_b128 v[154:157], v149 offset:2048
	ds_read_b128 v[158:161], v149 offset:3072
	v_add_u32_e32 v149, s54, v146
	ds_read_b128 v[162:165], v149
	ds_read_b128 v[180:183], v149 offset:1024
	ds_read_b128 v[184:187], v149 offset:2048
	ds_read_b128 v[188:191], v149 offset:3072
	v_lshl_add_u64 v[166:167], s[2:3], 0, v[138:139]
	s_add_i32 m0, s35, 0xc000
	ds_read_b128 v[192:195], v148
	ds_read_b128 v[196:199], v148 offset:1024
	ds_read_b128 v[200:203], v148 offset:2048
	ds_read_b128 v[204:207], v148 offset:3072
	ds_read_b128 v[224:227], v148 offset:4096
	ds_read_b128 v[228:231], v148 offset:5120
	ds_read_b128 v[232:235], v148 offset:6144
	ds_read_b128 v[236:239], v148 offset:7168
	global_load_lds_dwordx4 v[166:167], off
	v_lshl_add_u64 v[166:167], s[2:3], 0, v[140:141]
	s_add_i32 m0, s35, 0xe000
	s_nop 0
	global_load_lds_dwordx4 v[166:167], off
	s_waitcnt vmcnt(8)
	s_waitcnt lgkmcnt(0)
	s_barrier
	s_setprio 1
	s_waitcnt lgkmcnt(0)
	v_mfma_f32_16x16x32_bf16 v[128:131], v[142:145], v[192:195], v[128:131]
	v_mfma_f32_16x16x32_bf16 v[124:127], v[154:157], v[192:195], v[124:127]
	v_mfma_f32_16x16x32_bf16 v[112:115], v[142:145], v[200:203], v[112:115]
	v_mfma_f32_16x16x32_bf16 v[108:111], v[154:157], v[200:203], v[108:111]
	v_mfma_f32_16x16x32_bf16 v[96:99], v[142:145], v[224:227], v[96:99]
	v_mfma_f32_16x16x32_bf16 v[92:95], v[154:157], v[224:227], v[92:95]
	v_mfma_f32_16x16x32_bf16 v[80:83], v[142:145], v[232:235], v[80:83]
	v_mfma_f32_16x16x32_bf16 v[76:79], v[154:157], v[232:235], v[76:79]
	v_mfma_f32_16x16x32_bf16 v[128:131], v[150:153], v[196:199], v[128:131]
	v_mfma_f32_16x16x32_bf16 v[124:127], v[158:161], v[196:199], v[124:127]
	v_mfma_f32_16x16x32_bf16 v[112:115], v[150:153], v[204:207], v[112:115]
	v_mfma_f32_16x16x32_bf16 v[108:111], v[158:161], v[204:207], v[108:111]
	v_mfma_f32_16x16x32_bf16 v[96:99], v[150:153], v[228:231], v[96:99]
	v_mfma_f32_16x16x32_bf16 v[92:95], v[158:161], v[228:231], v[92:95]
	v_mfma_f32_16x16x32_bf16 v[80:83], v[150:153], v[236:239], v[80:83]
	v_mfma_f32_16x16x32_bf16 v[76:79], v[158:161], v[236:239], v[76:79]
	s_setprio 0
	s_setprio 1
	v_mfma_f32_16x16x32_bf16 v[120:123], v[162:165], v[192:195], v[120:123]
	v_mfma_f32_16x16x32_bf16 v[116:119], v[184:187], v[192:195], v[116:119]
	v_mfma_f32_16x16x32_bf16 v[104:107], v[162:165], v[200:203], v[104:107]
	v_mfma_f32_16x16x32_bf16 v[100:103], v[184:187], v[200:203], v[100:103]
	v_mfma_f32_16x16x32_bf16 v[88:91], v[162:165], v[224:227], v[88:91]
	v_mfma_f32_16x16x32_bf16 v[84:87], v[184:187], v[224:227], v[84:87]
	v_mfma_f32_16x16x32_bf16 v[72:75], v[162:165], v[232:235], v[72:75]
	v_mfma_f32_16x16x32_bf16 v[68:71], v[184:187], v[232:235], v[68:71]
	v_mfma_f32_16x16x32_bf16 v[120:123], v[180:183], v[196:199], v[120:123]
	v_mfma_f32_16x16x32_bf16 v[116:119], v[188:191], v[196:199], v[116:119]
	v_mfma_f32_16x16x32_bf16 v[104:107], v[180:183], v[204:207], v[104:107]
	v_mfma_f32_16x16x32_bf16 v[100:103], v[188:191], v[204:207], v[100:103]
	v_mfma_f32_16x16x32_bf16 v[88:91], v[180:183], v[228:231], v[88:91]
	v_mfma_f32_16x16x32_bf16 v[84:87], v[188:191], v[228:231], v[84:87]
	v_mfma_f32_16x16x32_bf16 v[72:75], v[180:183], v[236:239], v[72:75]
	v_mfma_f32_16x16x32_bf16 v[68:71], v[188:191], v[236:239], v[68:71]
	s_setprio 0
	s_barrier
	s_add_i32 s51, s51, s34
	v_lshl_add_u64 v[166:167], s[4:5], 0, v[34:35]
	s_mov_b32 m0, s51
	ds_read_b128 v[192:195], v148 offset:16384
	ds_read_b128 v[196:199], v148 offset:17408
	ds_read_b128 v[200:203], v148 offset:18432
	ds_read_b128 v[204:207], v148 offset:19456
	ds_read_b128 v[224:227], v148 offset:20480
	ds_read_b128 v[228:231], v148 offset:21504
	ds_read_b128 v[232:235], v148 offset:22528
	ds_read_b128 v[236:239], v148 offset:23552
	global_load_lds_dwordx4 v[166:167], off
	s_add_i32 m0, s51, 0x2000
	s_add_u32 s52, s4, 0x80000
	v_lshl_add_u64 v[168:169], s[4:5], 0, v[132:133]
	s_addc_u32 s53, s5, 0
	s_add_i32 s51, s54, s34
	global_load_lds_dwordx4 v[168:169], off
	v_lshl_add_u64 v[222:223], s[52:53], 0, v[34:35]
	s_mov_b32 m0, s51
	v_lshl_add_u64 v[240:241], s[26:27], 0, v[134:135]
	global_load_lds_dwordx4 v[222:223], off
	v_lshl_add_u64 v[222:223], s[52:53], 0, v[132:133]
	s_add_i32 m0, s51, 0x2000
	s_nop 0
	global_load_lds_dwordx4 v[222:223], off
	v_lshl_add_u64 v[222:223], s[26:27], 0, v[136:137]
	s_mov_b32 m0, s35
	s_nop 0
	global_load_lds_dwordx4 v[222:223], off
	s_mov_b32 m0, s36
	s_nop 0
	global_load_lds_dwordx4 v[240:241], off
	s_waitcnt vmcnt(8)
	s_waitcnt lgkmcnt(0)
	s_barrier
; #define PG8_STAGE(bufoff, gbase, voff) do { _Pragma("unroll") for (int _i = 0; _i < 2; ++_i) \
;         __builtin_amdgcn_global_load_lds((const unsigned*)((const char*)(gbase) + (voff)[_i]), (LAS unsigned*)(lds + (bufoff) + ldsw + _i * 8192), 16, 0, 0); } while (0)
; #define PG8_LDA(dst, b, h) do { _Pragma("unroll") for (int m = 0; m < 4; ++m) _Pragma("unroll") for (int k = 0; k < 2; ++k) dst[m][k] = *(const LAS bf16x8*)(lds + PG8_SA(b, h) + aoff + m * 2048 + k * 1024); } while (0)
; #define PG8_LDB(dst, b, h) do { _Pragma("unroll") for (int n = 0; n < 2; ++n) _Pragma("unroll") for (int k = 0; k < 2; ++k) dst[n][k] = *(const LAS bf16x8*)(lds + PG8_SB(b, h) + boff + n * 2048 + k * 1024); } while (0)
; #define PG8_MMA(ai, bj, At, Bt) do { __builtin_amdgcn_s_setprio(1); _Pragma("unroll") for (int m = 0; m < 4; ++m) _Pragma("unroll") for (int n = 0; n < 2; ++n) _Pragma("unroll") for (int k = 0; k < 2; ++k) \
;         acc[ai][bj][m][n] = __builtin_amdgcn_mfma_f32_16x16x32_bf16(Bt[n][k], At[m][k], acc[ai][bj][m][n], 0, 0, 0); __builtin_amdgcn_s_setprio(0); } while (0)
; #define PG8_WAIT_V(n) asm volatile("s_waitcnt vmcnt(" #n ")" ::: "memory")
; #define PG8_WAIT_L(n) asm volatile("s_waitcnt lgkmcnt(" #n ")" ::: "memory")
; #define PG8_BAR __builtin_amdgcn_s_barrier()
; #define PG8_SCHED __builtin_amdgcn_sched_barrier(0)
;     ...
;             PG8_WAIT_V(8); PG8_WAIT_L(0); PG8_BAR; PG8_MMA(1, 0, At, B0); PG8_MMA(1, 1, At, B1); PG8_BAR; PG8_SCHED;
;             PG8_LDB(B0, 1, 0); PG8_LDB(B1, 1, 1); PG8_SCHED; PG8_LDA(At, 1, 0); PG8_STAGE(PG8_SA(0, 1), a2 + hstep, voffA);
;             PG8_WAIT_V(8); PG8_WAIT_L(0); PG8_BAR; PG8_MMA(0, 0, At, B0); PG8_MMA(0, 1, At, B1); PG8_BAR; PG8_SCHED;
	s_setprio 1
	s_waitcnt lgkmcnt(0)
	v_mfma_f32_16x16x32_bf16 v[64:67], v[142:145], v[192:195], v[64:67]
	v_mfma_f32_16x16x32_bf16 v[60:63], v[154:157], v[192:195], v[60:63]
	v_mfma_f32_16x16x32_bf16 v[48:51], v[142:145], v[200:203], v[48:51]
	v_mfma_f32_16x16x32_bf16 v[44:47], v[154:157], v[200:203], v[44:47]
	v_mfma_f32_16x16x32_bf16 v[30:33], v[142:145], v[224:227], v[30:33]
	v_mfma_f32_16x16x32_bf16 v[26:29], v[154:157], v[224:227], v[26:29]
	v_mfma_f32_16x16x32_bf16 v[14:17], v[142:145], v[232:235], v[14:17]
	v_mfma_f32_16x16x32_bf16 v[10:13], v[154:157], v[232:235], v[10:13]
	v_mfma_f32_16x16x32_bf16 v[64:67], v[150:153], v[196:199], v[64:67]
	v_mfma_f32_16x16x32_bf16 v[60:63], v[158:161], v[196:199], v[60:63]
	v_mfma_f32_16x16x32_bf16 v[48:51], v[150:153], v[204:207], v[48:51]
	v_mfma_f32_16x16x32_bf16 v[44:47], v[158:161], v[204:207], v[44:47]
	v_mfma_f32_16x16x32_bf16 v[30:33], v[150:153], v[228:231], v[30:33]
	v_mfma_f32_16x16x32_bf16 v[26:29], v[158:161], v[228:231], v[26:29]
	v_mfma_f32_16x16x32_bf16 v[14:17], v[150:153], v[236:239], v[14:17]
	v_mfma_f32_16x16x32_bf16 v[10:13], v[158:161], v[236:239], v[10:13]
	s_setprio 0
	s_setprio 1
	v_mfma_f32_16x16x32_bf16 v[56:59], v[162:165], v[192:195], v[56:59]
	v_mfma_f32_16x16x32_bf16 v[52:55], v[184:187], v[192:195], v[52:55]
	v_mfma_f32_16x16x32_bf16 v[40:43], v[162:165], v[200:203], v[40:43]
	v_mfma_f32_16x16x32_bf16 v[36:39], v[184:187], v[200:203], v[36:39]
	v_mfma_f32_16x16x32_bf16 v[22:25], v[162:165], v[224:227], v[22:25]
	v_mfma_f32_16x16x32_bf16 v[18:21], v[184:187], v[224:227], v[18:21]
	v_mfma_f32_16x16x32_bf16 v[6:9], v[162:165], v[232:235], v[6:9]
	v_mfma_f32_16x16x32_bf16 v[2:5], v[184:187], v[232:235], v[2:5]
	v_mfma_f32_16x16x32_bf16 v[56:59], v[180:183], v[196:199], v[56:59]
	v_mfma_f32_16x16x32_bf16 v[52:55], v[188:191], v[196:199], v[52:55]
	v_mfma_f32_16x16x32_bf16 v[40:43], v[180:183], v[204:207], v[40:43]
	v_mfma_f32_16x16x32_bf16 v[36:39], v[188:191], v[204:207], v[36:39]
	v_mfma_f32_16x16x32_bf16 v[22:25], v[180:183], v[228:231], v[22:25]
	v_mfma_f32_16x16x32_bf16 v[18:21], v[188:191], v[228:231], v[18:21]
	v_mfma_f32_16x16x32_bf16 v[6:9], v[180:183], v[236:239], v[6:9]
	v_mfma_f32_16x16x32_bf16 v[2:5], v[188:191], v[236:239], v[2:5]
	s_setprio 0
	s_barrier
	s_add_i32 s51, 0, 0x18000
	v_add_u32_e32 v149, s51, v146
	s_add_i32 s52, 0, 0x1c000
	ds_read_b128 v[142:145], v149
	ds_read_b128 v[150:153], v149 offset:1024
	ds_read_b128 v[154:157], v149 offset:2048
	ds_read_b128 v[158:161], v149 offset:3072
	v_add_u32_e32 v149, s52, v146
	ds_read_b128 v[162:165], v149
	ds_read_b128 v[180:183], v149 offset:1024
	ds_read_b128 v[184:187], v149 offset:2048
	ds_read_b128 v[188:191], v149 offset:3072
	s_add_u32 s26, s26, 0x80000
	s_addc_u32 s27, s27, 0
	s_mov_b32 m0, s37
	v_lshl_add_u64 v[242:243], s[26:27], 0, v[136:137]
	ds_read_b128 v[192:195], v148 offset:32768
	ds_read_b128 v[196:199], v148 offset:33792
	ds_read_b128 v[200:203], v148 offset:34816
	ds_read_b128 v[204:207], v148 offset:35840
	ds_read_b128 v[224:227], v148 offset:36864
	ds_read_b128 v[228:231], v148 offset:37888
	ds_read_b128 v[232:235], v148 offset:38912
	ds_read_b128 v[236:239], v148 offset:39936
	global_load_lds_dwordx4 v[242:243], off
	v_lshl_add_u64 v[242:243], s[26:27], 0, v[134:135]
	s_mov_b32 m0, s44
	s_nop 0
	global_load_lds_dwordx4 v[242:243], off
	s_waitcnt vmcnt(8)
	s_waitcnt lgkmcnt(0)
	s_barrier
	s_setprio 1
	s_waitcnt lgkmcnt(0)
	v_mfma_f32_16x16x32_bf16 v[128:131], v[142:145], v[192:195], v[128:131]
	v_mfma_f32_16x16x32_bf16 v[124:127], v[154:157], v[192:195], v[124:127]
	v_mfma_f32_16x16x32_bf16 v[112:115], v[142:145], v[200:203], v[112:115]
	v_mfma_f32_16x16x32_bf16 v[108:111], v[154:157], v[200:203], v[108:111]
	v_mfma_f32_16x16x32_bf16 v[96:99], v[142:145], v[224:227], v[96:99]
	v_mfma_f32_16x16x32_bf16 v[92:95], v[154:157], v[224:227], v[92:95]
	v_mfma_f32_16x16x32_bf16 v[80:83], v[142:145], v[232:235], v[80:83]
	v_mfma_f32_16x16x32_bf16 v[76:79], v[154:157], v[232:235], v[76:79]
	v_mfma_f32_16x16x32_bf16 v[128:131], v[150:153], v[196:199], v[128:131]
	v_mfma_f32_16x16x32_bf16 v[124:127], v[158:161], v[196:199], v[124:127]
	v_mfma_f32_16x16x32_bf16 v[112:115], v[150:153], v[204:207], v[112:115]
	v_mfma_f32_16x16x32_bf16 v[108:111], v[158:161], v[204:207], v[108:111]
	v_mfma_f32_16x16x32_bf16 v[96:99], v[150:153], v[228:231], v[96:99]
	v_mfma_f32_16x16x32_bf16 v[92:95], v[158:161], v[228:231], v[92:95]
	v_mfma_f32_16x16x32_bf16 v[80:83], v[150:153], v[236:239], v[80:83]
	v_mfma_f32_16x16x32_bf16 v[76:79], v[158:161], v[236:239], v[76:79]
	s_setprio 0
	s_setprio 1
	v_mfma_f32_16x16x32_bf16 v[120:123], v[162:165], v[192:195], v[120:123]
	v_mfma_f32_16x16x32_bf16 v[116:119], v[184:187], v[192:195], v[116:119]
	v_mfma_f32_16x16x32_bf16 v[104:107], v[162:165], v[200:203], v[104:107]
	v_mfma_f32_16x16x32_bf16 v[100:103], v[184:187], v[200:203], v[100:103]
	v_mfma_f32_16x16x32_bf16 v[88:91], v[162:165], v[224:227], v[88:91]
	v_mfma_f32_16x16x32_bf16 v[84:87], v[184:187], v[224:227], v[84:87]
	v_mfma_f32_16x16x32_bf16 v[72:75], v[162:165], v[232:235], v[72:75]
	v_mfma_f32_16x16x32_bf16 v[68:71], v[184:187], v[232:235], v[68:71]
	v_mfma_f32_16x16x32_bf16 v[120:123], v[180:183], v[196:199], v[120:123]
	v_mfma_f32_16x16x32_bf16 v[116:119], v[188:191], v[196:199], v[116:119]
	v_mfma_f32_16x16x32_bf16 v[104:107], v[180:183], v[204:207], v[104:107]
	v_mfma_f32_16x16x32_bf16 v[100:103], v[188:191], v[204:207], v[100:103]
	v_mfma_f32_16x16x32_bf16 v[88:91], v[180:183], v[228:231], v[88:91]
	v_mfma_f32_16x16x32_bf16 v[84:87], v[188:191], v[228:231], v[84:87]
	v_mfma_f32_16x16x32_bf16 v[72:75], v[180:183], v[236:239], v[72:75]
	v_mfma_f32_16x16x32_bf16 v[68:71], v[188:191], v[236:239], v[68:71]
	s_setprio 0
	s_barrier
; #define PG8_STAGE(bufoff, gbase, voff) do { _Pragma("unroll") for (int _i = 0; _i < 2; ++_i) \
;         __builtin_amdgcn_global_load_lds((const unsigned*)((const char*)(gbase) + (voff)[_i]), (LAS unsigned*)(lds + (bufoff) + ldsw + _i * 8192), 16, 0, 0); } while (0)
; #define PG8_LDA(dst, b, h) do { _Pragma("unroll") for (int m = 0; m < 4; ++m) _Pragma("unroll") for (int k = 0; k < 2; ++k) dst[m][k] = *(const LAS bf16x8*)(lds + PG8_SA(b, h) + aoff + m * 2048 + k * 1024); } while (0)
; #define PG8_MMA(ai, bj, At, Bt) do { __builtin_amdgcn_s_setprio(1); _Pragma("unroll") for (int m = 0; m < 4; ++m) _Pragma("unroll") for (int n = 0; n < 2; ++n) _Pragma("unroll") for (int k = 0; k < 2; ++k) \
;         acc[ai][bj][m][n] = __builtin_amdgcn_mfma_f32_16x16x32_bf16(Bt[n][k], At[m][k], acc[ai][bj][m][n], 0, 0, 0); __builtin_amdgcn_s_setprio(0); } while (0)
; #define PG8_WAIT_V(n) asm volatile("s_waitcnt vmcnt(" #n ")" ::: "memory")
; #define PG8_WAIT_L(n) asm volatile("s_waitcnt lgkmcnt(" #n ")" ::: "memory")
; #define PG8_BAR __builtin_amdgcn_s_barrier()
; #define PG8_SCHED __builtin_amdgcn_sched_barrier(0)
;     ...
;         for (int t = 0; t < nt; t += 2) {
;             const bool last = (t == nt - 2);
;             const char* a1 = cA + (size_t)(t + 1) * kstep;
;             const char* a2 = last ? nA : cA + (size_t)(t + 2) * kstep; const char* b2 = last ? nB : cB + (size_t)(t + 2) * kstep;
;             const char* a3 = a2 + kstep; const char* b3 = b2 + kstep;
;     ...
;             PG8_LDA(At, 1, 1); PG8_STAGE(PG8_SB(1, 0), b3, voffB); PG8_STAGE(PG8_SB(1, 1), b3 + hstep, voffB); PG8_STAGE(PG8_SA(1, 0), a3, voffA);
;             PG8_WAIT_V(8); PG8_WAIT_L(0); PG8_BAR; PG8_MMA(1, 0, At, B0); PG8_MMA(1, 1, At, B1); PG8_BAR; PG8_SCHED;
	s_add_i32 s26, s51, s34
	v_lshl_add_u64 v[166:167], v[166:167], 0, s[22:23]
	s_mov_b32 m0, s26
	ds_read_b128 v[192:195], v148 offset:49152
	ds_read_b128 v[196:199], v148 offset:50176
	ds_read_b128 v[200:203], v148 offset:51200
	ds_read_b128 v[204:207], v148 offset:52224
	ds_read_b128 v[224:227], v148 offset:53248
	ds_read_b128 v[228:231], v148 offset:54272
	ds_read_b128 v[232:235], v148 offset:55296
	ds_read_b128 v[236:239], v148 offset:56320
	global_load_lds_dwordx4 v[166:167], off
	s_add_i32 m0, s26, 0x2000
	s_add_u32 s4, s4, 0x80080
	v_lshl_add_u64 v[166:167], v[168:169], 0, s[22:23]
	s_addc_u32 s5, s5, 0
	s_add_i32 s26, s52, s34
	global_load_lds_dwordx4 v[166:167], off
	v_lshl_add_u64 v[166:167], s[4:5], 0, v[34:35]
	s_mov_b32 m0, s26
	s_nop 0
	global_load_lds_dwordx4 v[166:167], off
	v_lshl_add_u64 v[166:167], s[4:5], 0, v[132:133]
	s_add_i32 m0, s26, 0x2000
	s_nop 0
	global_load_lds_dwordx4 v[166:167], off
	v_lshl_add_u64 v[166:167], v[222:223], 0, s[22:23]
	s_mov_b32 m0, s45
	s_nop 0
	global_load_lds_dwordx4 v[166:167], off
	v_lshl_add_u64 v[166:167], v[240:241], 0, s[22:23]
	s_mov_b32 m0, s46
	s_nop 0
	global_load_lds_dwordx4 v[166:167], off
	s_waitcnt vmcnt(8)
	s_waitcnt lgkmcnt(0)
	s_barrier
	s_setprio 1
	s_waitcnt lgkmcnt(0)
	v_mfma_f32_16x16x32_bf16 v[64:67], v[142:145], v[192:195], v[64:67]
	v_mfma_f32_16x16x32_bf16 v[60:63], v[154:157], v[192:195], v[60:63]
	v_mfma_f32_16x16x32_bf16 v[48:51], v[142:145], v[200:203], v[48:51]
	v_mfma_f32_16x16x32_bf16 v[44:47], v[154:157], v[200:203], v[44:47]
	v_mfma_f32_16x16x32_bf16 v[30:33], v[142:145], v[224:227], v[30:33]
	v_mfma_f32_16x16x32_bf16 v[26:29], v[154:157], v[224:227], v[26:29]
	v_mfma_f32_16x16x32_bf16 v[14:17], v[142:145], v[232:235], v[14:17]
	v_mfma_f32_16x16x32_bf16 v[10:13], v[154:157], v[232:235], v[10:13]
	v_mfma_f32_16x16x32_bf16 v[64:67], v[150:153], v[196:199], v[64:67]
	v_mfma_f32_16x16x32_bf16 v[60:63], v[158:161], v[196:199], v[60:63]
	v_mfma_f32_16x16x32_bf16 v[48:51], v[150:153], v[204:207], v[48:51]
	v_mfma_f32_16x16x32_bf16 v[44:47], v[158:161], v[204:207], v[44:47]
	v_mfma_f32_16x16x32_bf16 v[30:33], v[150:153], v[228:231], v[30:33]
	v_mfma_f32_16x16x32_bf16 v[26:29], v[158:161], v[228:231], v[26:29]
	v_mfma_f32_16x16x32_bf16 v[14:17], v[150:153], v[236:239], v[14:17]
	v_mfma_f32_16x16x32_bf16 v[10:13], v[158:161], v[236:239], v[10:13]
	s_setprio 0
	s_setprio 1
	v_mfma_f32_16x16x32_bf16 v[56:59], v[162:165], v[192:195], v[56:59]
	v_mfma_f32_16x16x32_bf16 v[52:55], v[184:187], v[192:195], v[52:55]
	v_mfma_f32_16x16x32_bf16 v[40:43], v[162:165], v[200:203], v[40:43]
	v_mfma_f32_16x16x32_bf16 v[36:39], v[184:187], v[200:203], v[36:39]
	v_mfma_f32_16x16x32_bf16 v[22:25], v[162:165], v[224:227], v[22:25]
	v_mfma_f32_16x16x32_bf16 v[18:21], v[184:187], v[224:227], v[18:21]
	v_mfma_f32_16x16x32_bf16 v[6:9], v[162:165], v[232:235], v[6:9]
	v_mfma_f32_16x16x32_bf16 v[2:5], v[184:187], v[232:235], v[2:5]
	v_mfma_f32_16x16x32_bf16 v[56:59], v[180:183], v[196:199], v[56:59]
	v_mfma_f32_16x16x32_bf16 v[52:55], v[188:191], v[196:199], v[52:55]
	v_mfma_f32_16x16x32_bf16 v[40:43], v[180:183], v[204:207], v[40:43]
	v_mfma_f32_16x16x32_bf16 v[36:39], v[188:191], v[204:207], v[36:39]
	v_mfma_f32_16x16x32_bf16 v[22:25], v[180:183], v[228:231], v[22:25]
	v_mfma_f32_16x16x32_bf16 v[18:21], v[188:191], v[228:231], v[18:21]
	v_mfma_f32_16x16x32_bf16 v[6:9], v[180:183], v[236:239], v[6:9]
	v_mfma_f32_16x16x32_bf16 v[2:5], v[188:191], v[236:239], v[2:5]
	s_setprio 0
	s_add_i32 s50, s50, 2
	s_add_u32 s2, s2, 0x100
	s_addc_u32 s3, s3, 0
	s_add_u32 s48, s48, 0x100
	s_addc_u32 s49, s49, 0
	s_add_u32 s4, s2, 0xfff80080
	s_addc_u32 s5, s3, -1
	s_add_i32 s51, 0, 0x10000
	s_cmp_eq_u32 s50, 28
	s_cselect_b32 s27, s19, s5
	s_cselect_b32 s26, s31, s4
	s_cselect_b32 s5, s17, s49
	s_cselect_b32 s4, s33, s48
	s_add_i32 s54, 0, 0x14000
	s_cmp_gt_u32 s50, 29
	s_barrier
	s_cbranch_scc0 .Lkrot_2
	s_and_b64 vcc, exec, s[14:15]
	s_cbranch_vccz .LBB0_1608
	s_barrier

; #define PG8_STAGE(bufoff, gbase, voff) do { _Pragma("unroll") for (int _i = 0; _i < 2; ++_i) \
;         __builtin_amdgcn_global_load_lds((const unsigned*)((const char*)(gbase) + (voff)[_i]), (LAS unsigned*)(lds + (bufoff) + ldsw + _i * 8192), 16, 0, 0); } while (0)
; #define PG8_LDA(dst, b, h) do { _Pragma("unroll") for (int m = 0; m < 4; ++m) _Pragma("unroll") for (int k = 0; k < 2; ++k) dst[m][k] = *(const LAS bf16x8*)(lds + PG8_SA(b, h) + aoff + m * 2048 + k * 1024); } while (0)
; #define PG8_LDB(dst, b, h) do { _Pragma("unroll") for (int n = 0; n < 2; ++n) _Pragma("unroll") for (int k = 0; k < 2; ++k) dst[n][k] = *(const LAS bf16x8*)(lds + PG8_SB(b, h) + boff + n * 2048 + k * 1024); } while (0)
; #define PG8_MMA(ai, bj, At, Bt) do { __builtin_amdgcn_s_setprio(1); _Pragma("unroll") for (int m = 0; m < 4; ++m) _Pragma("unroll") for (int n = 0; n < 2; ++n) _Pragma("unroll") for (int k = 0; k < 2; ++k) \
;         acc[ai][bj][m][n] = __builtin_amdgcn_mfma_f32_16x16x32_bf16(Bt[n][k], At[m][k], acc[ai][bj][m][n], 0, 0, 0); __builtin_amdgcn_s_setprio(0); } while (0)
; #define PG8_WAIT_V(n) asm volatile("s_waitcnt vmcnt(" #n ")" ::: "memory")
; #define PG8_WAIT_L(n) asm volatile("s_waitcnt lgkmcnt(" #n ")" ::: "memory")
; #define PG8_BAR __builtin_amdgcn_s_barrier()
; #define PG8_SCHED __builtin_amdgcn_sched_barrier(0)
;     ...
;             PG8_LDB(B0, 0, 0); PG8_LDB(B1, 0, 1); PG8_SCHED; PG8_LDA(At, 0, 0); PG8_STAGE(PG8_SA(1, 1), a1 + hstep, voffA);
;             PG8_WAIT_V(8); PG8_WAIT_L(0); PG8_BAR; PG8_MMA(0, 0, At, B0); PG8_MMA(0, 1, At, B1); PG8_BAR; PG8_SCHED;
;             PG8_LDA(At, 0, 1); PG8_STAGE(PG8_SB(0, 0), b2, voffB); PG8_STAGE(PG8_SB(0, 1), b2 + hstep, voffB); PG8_STAGE(PG8_SA(0, 0), a2, voffA);
.Lkrot_3:
	v_add_u32_e32 v154, s65, v185
	v_add_u32_e32 v166, s66, v185
	ds_read_b128 v[132:135], v154
	ds_read_b128 v[136:139], v154 offset:1024
	ds_read_b128 v[140:143], v154 offset:2048
	ds_read_b128 v[154:157], v154 offset:3072
	ds_read_b128 v[158:161], v166
	ds_read_b128 v[162:165], v166 offset:1024
	ds_read_b128 v[180:183], v166 offset:2048
	ds_read_b128 v[188:191], v166 offset:3072
	v_lshl_add_u64 v[166:167], s[2:3], 0, v[150:151]
	s_add_i32 m0, s29, 0xc000
	ds_read_b128 v[192:195], v187
	ds_read_b128 v[196:199], v187 offset:1024
	ds_read_b128 v[200:203], v187 offset:2048
	ds_read_b128 v[204:207], v187 offset:3072
	ds_read_b128 v[224:227], v187 offset:4096
	ds_read_b128 v[228:231], v187 offset:5120
	ds_read_b128 v[232:235], v187 offset:6144
	ds_read_b128 v[236:239], v187 offset:7168
	global_load_lds_dwordx4 v[166:167], off
	v_lshl_add_u64 v[166:167], s[2:3], 0, v[152:153]
	s_add_i32 m0, s29, 0xe000
	s_nop 0
	global_load_lds_dwordx4 v[166:167], off
	s_waitcnt vmcnt(8)
	s_waitcnt lgkmcnt(0)
	s_barrier
	s_setprio 1
	s_waitcnt lgkmcnt(0)
	v_mfma_f32_16x16x32_bf16 v[128:131], v[132:135], v[192:195], v[128:131]
	v_mfma_f32_16x16x32_bf16 v[124:127], v[140:143], v[192:195], v[124:127]
	v_mfma_f32_16x16x32_bf16 v[112:115], v[132:135], v[200:203], v[112:115]
	v_mfma_f32_16x16x32_bf16 v[108:111], v[140:143], v[200:203], v[108:111]
	v_mfma_f32_16x16x32_bf16 v[96:99], v[132:135], v[224:227], v[96:99]
	v_mfma_f32_16x16x32_bf16 v[92:95], v[140:143], v[224:227], v[92:95]
	v_mfma_f32_16x16x32_bf16 v[80:83], v[132:135], v[232:235], v[80:83]
	v_mfma_f32_16x16x32_bf16 v[76:79], v[140:143], v[232:235], v[76:79]
	v_mfma_f32_16x16x32_bf16 v[128:131], v[136:139], v[196:199], v[128:131]
	v_mfma_f32_16x16x32_bf16 v[124:127], v[154:157], v[196:199], v[124:127]
	v_mfma_f32_16x16x32_bf16 v[112:115], v[136:139], v[204:207], v[112:115]
	v_mfma_f32_16x16x32_bf16 v[108:111], v[154:157], v[204:207], v[108:111]
	v_mfma_f32_16x16x32_bf16 v[96:99], v[136:139], v[228:231], v[96:99]
	v_mfma_f32_16x16x32_bf16 v[92:95], v[154:157], v[228:231], v[92:95]
	v_mfma_f32_16x16x32_bf16 v[80:83], v[136:139], v[236:239], v[80:83]
	v_mfma_f32_16x16x32_bf16 v[76:79], v[154:157], v[236:239], v[76:79]
	s_setprio 0
	s_setprio 1
	v_mfma_f32_16x16x32_bf16 v[120:123], v[158:161], v[192:195], v[120:123]
	v_mfma_f32_16x16x32_bf16 v[116:119], v[180:183], v[192:195], v[116:119]
	v_mfma_f32_16x16x32_bf16 v[104:107], v[158:161], v[200:203], v[104:107]
	v_mfma_f32_16x16x32_bf16 v[100:103], v[180:183], v[200:203], v[100:103]
	v_mfma_f32_16x16x32_bf16 v[88:91], v[158:161], v[224:227], v[88:91]
	v_mfma_f32_16x16x32_bf16 v[84:87], v[180:183], v[224:227], v[84:87]
	v_mfma_f32_16x16x32_bf16 v[72:75], v[158:161], v[232:235], v[72:75]
	v_mfma_f32_16x16x32_bf16 v[68:71], v[180:183], v[232:235], v[68:71]
	v_mfma_f32_16x16x32_bf16 v[120:123], v[162:165], v[196:199], v[120:123]
	v_mfma_f32_16x16x32_bf16 v[116:119], v[188:191], v[196:199], v[116:119]
	v_mfma_f32_16x16x32_bf16 v[104:107], v[162:165], v[204:207], v[104:107]
	v_mfma_f32_16x16x32_bf16 v[100:103], v[188:191], v[204:207], v[100:103]
	v_mfma_f32_16x16x32_bf16 v[88:91], v[162:165], v[228:231], v[88:91]
	v_mfma_f32_16x16x32_bf16 v[84:87], v[188:191], v[228:231], v[84:87]
	v_mfma_f32_16x16x32_bf16 v[72:75], v[162:165], v[236:239], v[72:75]
	v_mfma_f32_16x16x32_bf16 v[68:71], v[188:191], v[236:239], v[68:71]
	s_setprio 0
	s_barrier
	s_add_i32 s2, s65, s25
	v_lshl_add_u64 v[166:167], s[34:35], 0, v[34:35]
	s_mov_b32 m0, s2
	ds_read_b128 v[192:195], v187 offset:16384
	ds_read_b128 v[196:199], v187 offset:17408
	ds_read_b128 v[200:203], v187 offset:18432
	ds_read_b128 v[204:207], v187 offset:19456
	ds_read_b128 v[224:227], v187 offset:20480
	ds_read_b128 v[228:231], v187 offset:21504
	ds_read_b128 v[232:235], v187 offset:22528
	ds_read_b128 v[236:239], v187 offset:23552
	global_load_lds_dwordx4 v[166:167], off
	s_add_i32 m0, s2, 0x2000
	s_add_u32 s2, s34, 0x160000
	v_lshl_add_u64 v[168:169], s[34:35], 0, v[144:145]
	s_addc_u32 s3, s35, 0
	s_add_i32 s65, s66, s25
	global_load_lds_dwordx4 v[168:169], off
	v_lshl_add_u64 v[222:223], s[2:3], 0, v[34:35]
	s_mov_b32 m0, s65
	v_lshl_add_u64 v[240:241], s[36:37], 0, v[146:147]
	global_load_lds_dwordx4 v[222:223], off
	v_lshl_add_u64 v[222:223], s[2:3], 0, v[144:145]
	s_add_i32 m0, s65, 0x2000
	s_nop 0
	global_load_lds_dwordx4 v[222:223], off
	v_lshl_add_u64 v[222:223], s[36:37], 0, v[148:149]
	s_mov_b32 m0, s29
	s_nop 0
	global_load_lds_dwordx4 v[222:223], off
	s_mov_b32 m0, s60
	s_nop 0
	global_load_lds_dwordx4 v[240:241], off
	s_waitcnt vmcnt(8)
	s_waitcnt lgkmcnt(0)
	s_barrier
; #define PG8_STAGE(bufoff, gbase, voff) do { _Pragma("unroll") for (int _i = 0; _i < 2; ++_i) \
;         __builtin_amdgcn_global_load_lds((const unsigned*)((const char*)(gbase) + (voff)[_i]), (LAS unsigned*)(lds + (bufoff) + ldsw + _i * 8192), 16, 0, 0); } while (0)
; #define PG8_LDA(dst, b, h) do { _Pragma("unroll") for (int m = 0; m < 4; ++m) _Pragma("unroll") for (int k = 0; k < 2; ++k) dst[m][k] = *(const LAS bf16x8*)(lds + PG8_SA(b, h) + aoff + m * 2048 + k * 1024); } while (0)
; #define PG8_LDB(dst, b, h) do { _Pragma("unroll") for (int n = 0; n < 2; ++n) _Pragma("unroll") for (int k = 0; k < 2; ++k) dst[n][k] = *(const LAS bf16x8*)(lds + PG8_SB(b, h) + boff + n * 2048 + k * 1024); } while (0)
; #define PG8_MMA(ai, bj, At, Bt) do { __builtin_amdgcn_s_setprio(1); _Pragma("unroll") for (int m = 0; m < 4; ++m) _Pragma("unroll") for (int n = 0; n < 2; ++n) _Pragma("unroll") for (int k = 0; k < 2; ++k) \
;         acc[ai][bj][m][n] = __builtin_amdgcn_mfma_f32_16x16x32_bf16(Bt[n][k], At[m][k], acc[ai][bj][m][n], 0, 0, 0); __builtin_amdgcn_s_setprio(0); } while (0)
; #define PG8_WAIT_V(n) asm volatile("s_waitcnt vmcnt(" #n ")" ::: "memory")
; #define PG8_WAIT_L(n) asm volatile("s_waitcnt lgkmcnt(" #n ")" ::: "memory")
; #define PG8_BAR __builtin_amdgcn_s_barrier()
; #define PG8_SCHED __builtin_amdgcn_sched_barrier(0)
;     ...
;             PG8_WAIT_V(8); PG8_WAIT_L(0); PG8_BAR; PG8_MMA(1, 0, At, B0); PG8_MMA(1, 1, At, B1); PG8_BAR; PG8_SCHED;
;             PG8_LDB(B0, 1, 0); PG8_LDB(B1, 1, 1); PG8_SCHED; PG8_LDA(At, 1, 0); PG8_STAGE(PG8_SA(0, 1), a2 + hstep, voffA);
;             PG8_WAIT_V(8); PG8_WAIT_L(0); PG8_BAR; PG8_MMA(0, 0, At, B0); PG8_MMA(0, 1, At, B1); PG8_BAR; PG8_SCHED;
	s_setprio 1
	s_waitcnt lgkmcnt(0)
	v_mfma_f32_16x16x32_bf16 v[64:67], v[132:135], v[192:195], v[64:67]
	v_mfma_f32_16x16x32_bf16 v[60:63], v[140:143], v[192:195], v[60:63]
	v_mfma_f32_16x16x32_bf16 v[48:51], v[132:135], v[200:203], v[48:51]
	v_mfma_f32_16x16x32_bf16 v[44:47], v[140:143], v[200:203], v[44:47]
	v_mfma_f32_16x16x32_bf16 v[30:33], v[132:135], v[224:227], v[30:33]
	v_mfma_f32_16x16x32_bf16 v[26:29], v[140:143], v[224:227], v[26:29]
	v_mfma_f32_16x16x32_bf16 v[14:17], v[132:135], v[232:235], v[14:17]
	v_mfma_f32_16x16x32_bf16 v[10:13], v[140:143], v[232:235], v[10:13]
	v_mfma_f32_16x16x32_bf16 v[64:67], v[136:139], v[196:199], v[64:67]
	v_mfma_f32_16x16x32_bf16 v[60:63], v[154:157], v[196:199], v[60:63]
	v_mfma_f32_16x16x32_bf16 v[48:51], v[136:139], v[204:207], v[48:51]
	v_mfma_f32_16x16x32_bf16 v[44:47], v[154:157], v[204:207], v[44:47]
	v_mfma_f32_16x16x32_bf16 v[30:33], v[136:139], v[228:231], v[30:33]
	v_mfma_f32_16x16x32_bf16 v[26:29], v[154:157], v[228:231], v[26:29]
	v_mfma_f32_16x16x32_bf16 v[14:17], v[136:139], v[236:239], v[14:17]
	v_mfma_f32_16x16x32_bf16 v[10:13], v[154:157], v[236:239], v[10:13]
	s_setprio 0
	s_setprio 1
	v_mfma_f32_16x16x32_bf16 v[56:59], v[158:161], v[192:195], v[56:59]
	v_mfma_f32_16x16x32_bf16 v[52:55], v[180:183], v[192:195], v[52:55]
	v_mfma_f32_16x16x32_bf16 v[40:43], v[158:161], v[200:203], v[40:43]
	v_mfma_f32_16x16x32_bf16 v[36:39], v[180:183], v[200:203], v[36:39]
	v_mfma_f32_16x16x32_bf16 v[22:25], v[158:161], v[224:227], v[22:25]
	v_mfma_f32_16x16x32_bf16 v[18:21], v[180:183], v[224:227], v[18:21]
	v_mfma_f32_16x16x32_bf16 v[6:9], v[158:161], v[232:235], v[6:9]
	v_mfma_f32_16x16x32_bf16 v[2:5], v[180:183], v[232:235], v[2:5]
	v_mfma_f32_16x16x32_bf16 v[56:59], v[162:165], v[196:199], v[56:59]
	v_mfma_f32_16x16x32_bf16 v[52:55], v[188:191], v[196:199], v[52:55]
	v_mfma_f32_16x16x32_bf16 v[40:43], v[162:165], v[204:207], v[40:43]
	v_mfma_f32_16x16x32_bf16 v[36:39], v[188:191], v[204:207], v[36:39]
	v_mfma_f32_16x16x32_bf16 v[22:25], v[162:165], v[228:231], v[22:25]
	v_mfma_f32_16x16x32_bf16 v[18:21], v[188:191], v[228:231], v[18:21]
	v_mfma_f32_16x16x32_bf16 v[6:9], v[162:165], v[236:239], v[6:9]
	v_mfma_f32_16x16x32_bf16 v[2:5], v[188:191], v[236:239], v[2:5]
	s_setprio 0
	s_barrier
	s_add_i32 s65, 0, 0x18000
	s_add_i32 s66, 0, 0x1c000
	v_add_u32_e32 v154, s65, v185
	v_add_u32_e32 v188, s66, v185
	ds_read_b128 v[132:135], v154
	ds_read_b128 v[136:139], v154 offset:1024
	ds_read_b128 v[140:143], v154 offset:2048
	ds_read_b128 v[154:157], v154 offset:3072
	ds_read_b128 v[158:161], v188
	ds_read_b128 v[162:165], v188 offset:1024
	ds_read_b128 v[180:183], v188 offset:2048
	ds_read_b128 v[188:191], v188 offset:3072
	s_add_u32 s2, s36, 0x160000
	s_addc_u32 s3, s37, 0
	s_mov_b32 m0, s61
	v_lshl_add_u64 v[242:243], s[2:3], 0, v[148:149]
	ds_read_b128 v[192:195], v187 offset:32768
	ds_read_b128 v[196:199], v187 offset:33792
	ds_read_b128 v[200:203], v187 offset:34816
	ds_read_b128 v[204:207], v187 offset:35840
	ds_read_b128 v[224:227], v187 offset:36864
	ds_read_b128 v[228:231], v187 offset:37888
	ds_read_b128 v[232:235], v187 offset:38912
	ds_read_b128 v[236:239], v187 offset:39936
	global_load_lds_dwordx4 v[242:243], off
	v_lshl_add_u64 v[242:243], s[2:3], 0, v[146:147]
	s_mov_b32 m0, s62
	s_nop 0
	global_load_lds_dwordx4 v[242:243], off
	s_waitcnt vmcnt(8)
	s_waitcnt lgkmcnt(0)
	s_barrier
	s_setprio 1
	s_waitcnt lgkmcnt(0)
	v_mfma_f32_16x16x32_bf16 v[128:131], v[132:135], v[192:195], v[128:131]
	v_mfma_f32_16x16x32_bf16 v[124:127], v[140:143], v[192:195], v[124:127]
	v_mfma_f32_16x16x32_bf16 v[112:115], v[132:135], v[200:203], v[112:115]
	v_mfma_f32_16x16x32_bf16 v[108:111], v[140:143], v[200:203], v[108:111]
	v_mfma_f32_16x16x32_bf16 v[96:99], v[132:135], v[224:227], v[96:99]
	v_mfma_f32_16x16x32_bf16 v[92:95], v[140:143], v[224:227], v[92:95]
	v_mfma_f32_16x16x32_bf16 v[80:83], v[132:135], v[232:235], v[80:83]
	v_mfma_f32_16x16x32_bf16 v[76:79], v[140:143], v[232:235], v[76:79]
	v_mfma_f32_16x16x32_bf16 v[128:131], v[136:139], v[196:199], v[128:131]
	v_mfma_f32_16x16x32_bf16 v[124:127], v[154:157], v[196:199], v[124:127]
	v_mfma_f32_16x16x32_bf16 v[112:115], v[136:139], v[204:207], v[112:115]
	v_mfma_f32_16x16x32_bf16 v[108:111], v[154:157], v[204:207], v[108:111]
	v_mfma_f32_16x16x32_bf16 v[96:99], v[136:139], v[228:231], v[96:99]
	v_mfma_f32_16x16x32_bf16 v[92:95], v[154:157], v[228:231], v[92:95]
	v_mfma_f32_16x16x32_bf16 v[80:83], v[136:139], v[236:239], v[80:83]
	v_mfma_f32_16x16x32_bf16 v[76:79], v[154:157], v[236:239], v[76:79]
	s_setprio 0
	s_setprio 1
	v_mfma_f32_16x16x32_bf16 v[120:123], v[158:161], v[192:195], v[120:123]
	v_mfma_f32_16x16x32_bf16 v[116:119], v[180:183], v[192:195], v[116:119]
	v_mfma_f32_16x16x32_bf16 v[104:107], v[158:161], v[200:203], v[104:107]
	v_mfma_f32_16x16x32_bf16 v[100:103], v[180:183], v[200:203], v[100:103]
	v_mfma_f32_16x16x32_bf16 v[88:91], v[158:161], v[224:227], v[88:91]
	v_mfma_f32_16x16x32_bf16 v[84:87], v[180:183], v[224:227], v[84:87]
	v_mfma_f32_16x16x32_bf16 v[72:75], v[158:161], v[232:235], v[72:75]
	v_mfma_f32_16x16x32_bf16 v[68:71], v[180:183], v[232:235], v[68:71]
	v_mfma_f32_16x16x32_bf16 v[120:123], v[162:165], v[196:199], v[120:123]
	v_mfma_f32_16x16x32_bf16 v[116:119], v[188:191], v[196:199], v[116:119]
	v_mfma_f32_16x16x32_bf16 v[104:107], v[162:165], v[204:207], v[104:107]
	v_mfma_f32_16x16x32_bf16 v[100:103], v[188:191], v[204:207], v[100:103]
	v_mfma_f32_16x16x32_bf16 v[88:91], v[162:165], v[228:231], v[88:91]
	v_mfma_f32_16x16x32_bf16 v[84:87], v[188:191], v[228:231], v[84:87]
	v_mfma_f32_16x16x32_bf16 v[72:75], v[162:165], v[236:239], v[72:75]
	v_mfma_f32_16x16x32_bf16 v[68:71], v[188:191], v[236:239], v[68:71]
	s_setprio 0
	s_barrier
; #define PG8_STAGE(bufoff, gbase, voff) do { _Pragma("unroll") for (int _i = 0; _i < 2; ++_i) \
;         __builtin_amdgcn_global_load_lds((const unsigned*)((const char*)(gbase) + (voff)[_i]), (LAS unsigned*)(lds + (bufoff) + ldsw + _i * 8192), 16, 0, 0); } while (0)
; #define PG8_LDA(dst, b, h) do { _Pragma("unroll") for (int m = 0; m < 4; ++m) _Pragma("unroll") for (int k = 0; k < 2; ++k) dst[m][k] = *(const LAS bf16x8*)(lds + PG8_SA(b, h) + aoff + m * 2048 + k * 1024); } while (0)
; #define PG8_MMA(ai, bj, At, Bt) do { __builtin_amdgcn_s_setprio(1); _Pragma("unroll") for (int m = 0; m < 4; ++m) _Pragma("unroll") for (int n = 0; n < 2; ++n) _Pragma("unroll") for (int k = 0; k < 2; ++k) \
;         acc[ai][bj][m][n] = __builtin_amdgcn_mfma_f32_16x16x32_bf16(Bt[n][k], At[m][k], acc[ai][bj][m][n], 0, 0, 0); __builtin_amdgcn_s_setprio(0); } while (0)
; #define PG8_WAIT_V(n) asm volatile("s_waitcnt vmcnt(" #n ")" ::: "memory")
; #define PG8_WAIT_L(n) asm volatile("s_waitcnt lgkmcnt(" #n ")" ::: "memory")
; #define PG8_BAR __builtin_amdgcn_s_barrier()
; #define PG8_SCHED __builtin_amdgcn_sched_barrier(0)
;     ...
;         for (int t = 0; t < nt; t += 2) {
;             const bool last = (t == nt - 2);
;             const char* a1 = cA + (size_t)(t + 1) * kstep;
;             const char* a2 = last ? nA : cA + (size_t)(t + 2) * kstep; const char* b2 = last ? nB : cB + (size_t)(t + 2) * kstep;
;             const char* a3 = a2 + kstep; const char* b3 = b2 + kstep;
;     ...
;             PG8_LDA(At, 1, 1); PG8_STAGE(PG8_SB(1, 0), b3, voffB); PG8_STAGE(PG8_SB(1, 1), b3 + hstep, voffB); PG8_STAGE(PG8_SA(1, 0), a3, voffA);
;             PG8_WAIT_V(8); PG8_WAIT_L(0); PG8_BAR; PG8_MMA(1, 0, At, B0); PG8_MMA(1, 1, At, B1); PG8_BAR; PG8_SCHED;
	s_add_i32 s2, s65, s25
	v_lshl_add_u64 v[166:167], v[166:167], 0, s[22:23]
	s_mov_b32 m0, s2
	ds_read_b128 v[192:195], v187 offset:49152
	ds_read_b128 v[196:199], v187 offset:50176
	ds_read_b128 v[200:203], v187 offset:51200
	ds_read_b128 v[204:207], v187 offset:52224
	ds_read_b128 v[224:227], v187 offset:53248
	ds_read_b128 v[228:231], v187 offset:54272
	ds_read_b128 v[232:235], v187 offset:55296
	ds_read_b128 v[236:239], v187 offset:56320
	global_load_lds_dwordx4 v[166:167], off
	s_add_i32 m0, s2, 0x2000
	s_add_u32 s2, s34, 0x160080
	v_lshl_add_u64 v[166:167], v[168:169], 0, s[22:23]
	s_addc_u32 s3, s35, 0
	s_add_i32 s34, s66, s25
	global_load_lds_dwordx4 v[166:167], off
	v_lshl_add_u64 v[166:167], s[2:3], 0, v[34:35]
	s_mov_b32 m0, s34
	s_nop 0
	global_load_lds_dwordx4 v[166:167], off
	v_lshl_add_u64 v[166:167], s[2:3], 0, v[144:145]
	s_add_i32 m0, s34, 0x2000
	s_nop 0
	global_load_lds_dwordx4 v[166:167], off
	v_lshl_add_u64 v[166:167], v[222:223], 0, s[22:23]
	s_mov_b32 m0, s63
	s_nop 0
	global_load_lds_dwordx4 v[166:167], off
	v_lshl_add_u64 v[166:167], v[240:241], 0, s[22:23]
	s_mov_b32 m0, s64
	s_nop 0
	global_load_lds_dwordx4 v[166:167], off
	s_waitcnt vmcnt(8)
	s_waitcnt lgkmcnt(0)
	s_barrier
	s_setprio 1
	s_waitcnt lgkmcnt(0)
	v_mfma_f32_16x16x32_bf16 v[64:67], v[132:135], v[192:195], v[64:67]
	v_mfma_f32_16x16x32_bf16 v[60:63], v[140:143], v[192:195], v[60:63]
	v_mfma_f32_16x16x32_bf16 v[48:51], v[132:135], v[200:203], v[48:51]
	v_mfma_f32_16x16x32_bf16 v[44:47], v[140:143], v[200:203], v[44:47]
	v_mfma_f32_16x16x32_bf16 v[30:33], v[132:135], v[224:227], v[30:33]
	v_mfma_f32_16x16x32_bf16 v[26:29], v[140:143], v[224:227], v[26:29]
	v_mfma_f32_16x16x32_bf16 v[14:17], v[132:135], v[232:235], v[14:17]
	v_mfma_f32_16x16x32_bf16 v[10:13], v[140:143], v[232:235], v[10:13]
	v_mfma_f32_16x16x32_bf16 v[64:67], v[136:139], v[196:199], v[64:67]
	v_mfma_f32_16x16x32_bf16 v[60:63], v[154:157], v[196:199], v[60:63]
	v_mfma_f32_16x16x32_bf16 v[48:51], v[136:139], v[204:207], v[48:51]
	v_mfma_f32_16x16x32_bf16 v[44:47], v[154:157], v[204:207], v[44:47]
	v_mfma_f32_16x16x32_bf16 v[30:33], v[136:139], v[228:231], v[30:33]
	v_mfma_f32_16x16x32_bf16 v[26:29], v[154:157], v[228:231], v[26:29]
	v_mfma_f32_16x16x32_bf16 v[14:17], v[136:139], v[236:239], v[14:17]
	v_mfma_f32_16x16x32_bf16 v[10:13], v[154:157], v[236:239], v[10:13]
	s_setprio 0
	s_setprio 1
	v_mfma_f32_16x16x32_bf16 v[56:59], v[158:161], v[192:195], v[56:59]
	v_mfma_f32_16x16x32_bf16 v[52:55], v[180:183], v[192:195], v[52:55]
	v_mfma_f32_16x16x32_bf16 v[40:43], v[158:161], v[200:203], v[40:43]
	v_mfma_f32_16x16x32_bf16 v[36:39], v[180:183], v[200:203], v[36:39]
	v_mfma_f32_16x16x32_bf16 v[22:25], v[158:161], v[224:227], v[22:25]
	v_mfma_f32_16x16x32_bf16 v[18:21], v[180:183], v[224:227], v[18:21]
	v_mfma_f32_16x16x32_bf16 v[6:9], v[158:161], v[232:235], v[6:9]
	v_mfma_f32_16x16x32_bf16 v[2:5], v[180:183], v[232:235], v[2:5]
	v_mfma_f32_16x16x32_bf16 v[56:59], v[162:165], v[196:199], v[56:59]
	v_mfma_f32_16x16x32_bf16 v[52:55], v[188:191], v[196:199], v[52:55]
	v_mfma_f32_16x16x32_bf16 v[40:43], v[162:165], v[204:207], v[40:43]
	v_mfma_f32_16x16x32_bf16 v[36:39], v[188:191], v[204:207], v[36:39]
	v_mfma_f32_16x16x32_bf16 v[22:25], v[162:165], v[228:231], v[22:25]
	v_mfma_f32_16x16x32_bf16 v[18:21], v[188:191], v[228:231], v[18:21]
	v_mfma_f32_16x16x32_bf16 v[6:9], v[162:165], v[236:239], v[6:9]
	v_mfma_f32_16x16x32_bf16 v[2:5], v[188:191], v[236:239], v[2:5]
	s_setprio 0
	s_add_i32 s49, s49, 2
	s_add_u32 s47, s47, 0x100
	s_addc_u32 s48, s48, 0
	s_mov_b64 s[2:3], s[26:27]
	s_add_u32 s26, s2, 0x100
	s_addc_u32 s27, s3, 0
	s_add_i32 s65, 0, 0x10000
	s_cmpk_eq_i32 s49, 0x54
	s_cselect_b32 s37, s5, s27
	s_cselect_b32 s36, s4, s26
	s_cselect_b32 s35, s59, s48
	s_cselect_b32 s34, s58, s47
	s_add_i32 s66, 0, 0x14000
	s_cmpk_gt_u32 s49, 0x55
	s_barrier
	s_cbranch_scc0 .Lkrot_3
	s_and_b64 vcc, exec, s[52:53]
	s_cbranch_vccz .LBB0_1684
	s_barrier
